# back-edge rotation: loop-closing barrier becomes the loop head in the 5 GEMM K-loops and both attention KV loops (counter/exit test/branch before the barrier)
# speedup vs baseline: 1.0029x; 1.0029x over previous
.LBB0_266:
	s_ashr_i32 s43, s42, 31
	s_lshl_b64 s[44:45], s[42:43], 19
	s_add_u32 s44, s6, s44
	s_addc_u32 s45, s7, s45
	s_and_b64 s[46:47], s[0:1], exec
	s_cselect_b32 s43, s45, s53
	s_cselect_b32 s51, s44, s52
	s_ashr_i32 s41, s40, 31
	s_lshl_b64 s[46:47], s[40:41], 19
	s_add_u32 s46, s33, s46
	s_addc_u32 s47, s58, s47
	s_and_b64 s[56:57], s[0:1], exec
	s_cselect_b32 s41, s47, s55
	s_cselect_b32 s87, s46, s54
	s_add_u32 s52, s52, 0x40080
	s_addc_u32 s53, s53, 0
	s_add_u32 s96, s54, 0x100
	v_mov_b32_e32 v32, 0
	s_addc_u32 s97, s55, 0
	s_mov_b32 vcc_lo, -2
	v_mov_b32_e32 v33, v32
	v_mov_b32_e32 v34, v32
	v_mov_b32_e32 v35, v32
	v_mov_b32_e32 v36, v32
	v_mov_b32_e32 v37, v32
	v_mov_b32_e32 v38, v32
	v_mov_b32_e32 v39, v32
	v_mov_b32_e32 v64, v32
	v_mov_b32_e32 v65, v32
	v_mov_b32_e32 v66, v32
	v_mov_b32_e32 v67, v32
	v_mov_b32_e32 v72, v32
	v_mov_b32_e32 v73, v32
	v_mov_b32_e32 v74, v32
	v_mov_b32_e32 v75, v32
	v_mov_b32_e32 v80, v32
	v_mov_b32_e32 v81, v32
	v_mov_b32_e32 v82, v32
	v_mov_b32_e32 v83, v32
	v_mov_b32_e32 v84, v32
	v_mov_b32_e32 v85, v32
	v_mov_b32_e32 v86, v32
	v_mov_b32_e32 v87, v32
	v_mov_b32_e32 v88, v32
	v_mov_b32_e32 v89, v32
	v_mov_b32_e32 v90, v32
	v_mov_b32_e32 v91, v32
	v_mov_b32_e32 v92, v32
	v_mov_b32_e32 v93, v32
	v_mov_b32_e32 v94, v32
	v_mov_b32_e32 v95, v32
	v_mov_b32_e32 v0, v32
	v_mov_b32_e32 v1, v32
	v_mov_b32_e32 v2, v32
	v_mov_b32_e32 v3, v32
	v_mov_b32_e32 v4, v32
	v_mov_b32_e32 v5, v32
	v_mov_b32_e32 v6, v32
	v_mov_b32_e32 v7, v32
	v_mov_b32_e32 v8, v32
	v_mov_b32_e32 v9, v32
	v_mov_b32_e32 v10, v32
	v_mov_b32_e32 v11, v32
	v_mov_b32_e32 v12, v32
	v_mov_b32_e32 v13, v32
	v_mov_b32_e32 v14, v32
	v_mov_b32_e32 v15, v32
	v_mov_b32_e32 v16, v32
	v_mov_b32_e32 v17, v32
	v_mov_b32_e32 v18, v32
	v_mov_b32_e32 v19, v32
	v_mov_b32_e32 v20, v32
	v_mov_b32_e32 v21, v32
	v_mov_b32_e32 v22, v32
	v_mov_b32_e32 v23, v32
	v_mov_b32_e32 v24, v32
	v_mov_b32_e32 v25, v32
	v_mov_b32_e32 v26, v32
	v_mov_b32_e32 v27, v32
	v_mov_b32_e32 v28, v32
	v_mov_b32_e32 v29, v32
	v_mov_b32_e32 v30, v32
	v_mov_b32_e32 v31, v32
	v_mov_b32_e32 v96, v32
	v_mov_b32_e32 v97, v32
	v_mov_b32_e32 v98, v32
	v_mov_b32_e32 v99, v32
	v_mov_b32_e32 v100, v32
	v_mov_b32_e32 v101, v32
	v_mov_b32_e32 v102, v32
	v_mov_b32_e32 v103, v32
	v_mov_b32_e32 v104, v32
	v_mov_b32_e32 v105, v32
	v_mov_b32_e32 v106, v32
	v_mov_b32_e32 v107, v32
	v_mov_b32_e32 v108, v32
	v_mov_b32_e32 v109, v32
	v_mov_b32_e32 v110, v32
	v_mov_b32_e32 v111, v32
	v_mov_b32_e32 v112, v32
	v_mov_b32_e32 v113, v32
	v_mov_b32_e32 v114, v32
	v_mov_b32_e32 v115, v32
	v_mov_b32_e32 v116, v32
	v_mov_b32_e32 v117, v32
	v_mov_b32_e32 v118, v32
	v_mov_b32_e32 v119, v32
	v_mov_b32_e32 v120, v32
	v_mov_b32_e32 v121, v32
	v_mov_b32_e32 v122, v32
	v_mov_b32_e32 v123, v32
	v_mov_b32_e32 v124, v32
	v_mov_b32_e32 v125, v32
	v_mov_b32_e32 v126, v32
	v_mov_b32_e32 v127, v32
	v_mov_b32_e32 v40, v32
	v_mov_b32_e32 v41, v32
	v_mov_b32_e32 v42, v32
	v_mov_b32_e32 v43, v32
	v_mov_b32_e32 v44, v32
	v_mov_b32_e32 v45, v32
	v_mov_b32_e32 v46, v32
	v_mov_b32_e32 v47, v32
	v_mov_b32_e32 v48, v32
	v_mov_b32_e32 v49, v32
	v_mov_b32_e32 v50, v32
	v_mov_b32_e32 v51, v32
	v_mov_b32_e32 v52, v32
	v_mov_b32_e32 v53, v32
	v_mov_b32_e32 v54, v32
	v_mov_b32_e32 v55, v32
	v_mov_b32_e32 v56, v32
	v_mov_b32_e32 v57, v32
	v_mov_b32_e32 v58, v32
	v_mov_b32_e32 v59, v32
	v_mov_b32_e32 v60, v32
	v_mov_b32_e32 v61, v32
	v_mov_b32_e32 v62, v32
	v_mov_b32_e32 v63, v32
	v_mov_b32_e32 v68, v32
	v_mov_b32_e32 v69, v32
	v_mov_b32_e32 v70, v32
	v_mov_b32_e32 v71, v32
	v_mov_b32_e32 v76, v32
	v_mov_b32_e32 v77, v32
	v_mov_b32_e32 v78, v32
	v_mov_b32_e32 v79, v32
	s_branch .LBB0_267

.LBB0_267:
	ds_read_b128 v[128:131], v225
	ds_read_b128 v[132:135], v225 offset:1024
	ds_read_b128 v[136:139], v225 offset:2048
	ds_read_b128 v[140:143], v225 offset:3072
	ds_read_b128 v[144:147], v226
	ds_read_b128 v[148:151], v226 offset:1024
	ds_read_b128 v[152:155], v226 offset:2048
	ds_read_b128 v[156:159], v226 offset:3072
	s_add_u32 s20, s52, 0xfffc0080
	s_addc_u32 s21, s53, -1
	s_cmp_eq_u32 vcc_lo, 12
	s_cselect_b32 s57, s43, s21
	s_cselect_b32 s56, s51, s20
	s_cselect_b32 s55, s41, s97
	s_cselect_b32 s54, s87, s96
	v_lshl_add_u64 v[216:217], s[52:53], 0, v[206:207]
	s_add_i32 m0, s49, 0xc000
	ds_read_b128 v[160:163], v227
	ds_read_b128 v[164:167], v227 offset:1024
	ds_read_b128 v[168:171], v227 offset:2048
	ds_read_b128 v[172:175], v227 offset:3072
	ds_read_b128 v[176:179], v227 offset:4096
	ds_read_b128 v[180:183], v227 offset:5120
	ds_read_b128 v[184:187], v227 offset:6144
	ds_read_b128 v[188:191], v227 offset:7168
	global_load_lds_dwordx4 v[216:217], off
	v_lshl_add_u64 v[216:217], s[52:53], 0, v[210:211]
	s_add_i32 m0, s49, 0xe000
	s_nop 0
	global_load_lds_dwordx4 v[216:217], off
	s_waitcnt vmcnt(8)
	s_waitcnt lgkmcnt(0)
	s_barrier
	s_setprio 1
	s_waitcnt lgkmcnt(0)
	v_mfma_f32_16x16x32_bf16 v[76:79], v[128:131], v[160:163], v[76:79]
	v_mfma_f32_16x16x32_bf16 v[68:71], v[136:139], v[160:163], v[68:71]
	v_mfma_f32_16x16x32_bf16 v[60:63], v[128:131], v[168:171], v[60:63]
	v_mfma_f32_16x16x32_bf16 v[56:59], v[136:139], v[168:171], v[56:59]
	v_mfma_f32_16x16x32_bf16 v[52:55], v[128:131], v[176:179], v[52:55]
	v_mfma_f32_16x16x32_bf16 v[48:51], v[136:139], v[176:179], v[48:51]
	v_mfma_f32_16x16x32_bf16 v[44:47], v[128:131], v[184:187], v[44:47]
	v_mfma_f32_16x16x32_bf16 v[40:43], v[136:139], v[184:187], v[40:43]
	v_mfma_f32_16x16x32_bf16 v[76:79], v[132:135], v[164:167], v[76:79]
	v_mfma_f32_16x16x32_bf16 v[68:71], v[140:143], v[164:167], v[68:71]
	v_mfma_f32_16x16x32_bf16 v[60:63], v[132:135], v[172:175], v[60:63]
	v_mfma_f32_16x16x32_bf16 v[56:59], v[140:143], v[172:175], v[56:59]
	v_mfma_f32_16x16x32_bf16 v[52:55], v[132:135], v[180:183], v[52:55]
	v_mfma_f32_16x16x32_bf16 v[48:51], v[140:143], v[180:183], v[48:51]
	v_mfma_f32_16x16x32_bf16 v[44:47], v[132:135], v[188:191], v[44:47]
	v_mfma_f32_16x16x32_bf16 v[40:43], v[140:143], v[188:191], v[40:43]
	s_setprio 0
	s_setprio 1
	v_mfma_f32_16x16x32_bf16 v[124:127], v[144:147], v[160:163], v[124:127]
	v_mfma_f32_16x16x32_bf16 v[120:123], v[152:155], v[160:163], v[120:123]
	v_mfma_f32_16x16x32_bf16 v[116:119], v[144:147], v[168:171], v[116:119]
	v_mfma_f32_16x16x32_bf16 v[112:115], v[152:155], v[168:171], v[112:115]
	v_mfma_f32_16x16x32_bf16 v[108:111], v[144:147], v[176:179], v[108:111]
	v_mfma_f32_16x16x32_bf16 v[104:107], v[152:155], v[176:179], v[104:107]
	v_mfma_f32_16x16x32_bf16 v[100:103], v[144:147], v[184:187], v[100:103]
	v_mfma_f32_16x16x32_bf16 v[96:99], v[152:155], v[184:187], v[96:99]
	v_mfma_f32_16x16x32_bf16 v[124:127], v[148:151], v[164:167], v[124:127]
	v_mfma_f32_16x16x32_bf16 v[120:123], v[156:159], v[164:167], v[120:123]
	v_mfma_f32_16x16x32_bf16 v[116:119], v[148:151], v[172:175], v[116:119]
	v_mfma_f32_16x16x32_bf16 v[112:115], v[156:159], v[172:175], v[112:115]
	v_mfma_f32_16x16x32_bf16 v[108:111], v[148:151], v[180:183], v[108:111]
	v_mfma_f32_16x16x32_bf16 v[104:107], v[156:159], v[180:183], v[104:107]
	v_mfma_f32_16x16x32_bf16 v[100:103], v[148:151], v[188:191], v[100:103]
	v_mfma_f32_16x16x32_bf16 v[96:99], v[156:159], v[188:191], v[96:99]
	s_setprio 0
	s_barrier
	s_add_i32 s20, s84, s3
	v_lshl_add_u64 v[216:217], s[54:55], 0, v[194:195]
	s_mov_b32 m0, s20
	ds_read_b128 v[160:163], v227 offset:16384
	ds_read_b128 v[164:167], v227 offset:17408
	ds_read_b128 v[168:171], v227 offset:18432
	ds_read_b128 v[172:175], v227 offset:19456
	ds_read_b128 v[176:179], v227 offset:20480
	ds_read_b128 v[180:183], v227 offset:21504
	ds_read_b128 v[184:187], v227 offset:22528
	ds_read_b128 v[188:191], v227 offset:23552
	global_load_lds_dwordx4 v[216:217], off
	s_add_i32 m0, s20, 0x2000
	s_add_u32 s20, s54, 0x40000
	v_lshl_add_u64 v[218:219], s[54:55], 0, v[198:199]
	s_addc_u32 s21, s55, 0
	s_add_i32 vcc_hi, s85, s3
	global_load_lds_dwordx4 v[218:219], off
	v_lshl_add_u64 v[220:221], s[20:21], 0, v[194:195]
	s_mov_b32 m0, vcc_hi
	v_lshl_add_u64 v[222:223], s[56:57], 0, v[196:197]
	global_load_lds_dwordx4 v[220:221], off
	v_lshl_add_u64 v[220:221], s[20:21], 0, v[198:199]
	s_add_i32 m0, vcc_hi, 0x2000
	s_nop 0
	global_load_lds_dwordx4 v[220:221], off
	v_lshl_add_u64 v[220:221], s[56:57], 0, v[192:193]
	s_mov_b32 m0, s49
	s_nop 0
	global_load_lds_dwordx4 v[220:221], off
	s_mov_b32 m0, s59
	s_nop 0
	global_load_lds_dwordx4 v[222:223], off
	s_waitcnt vmcnt(8)
	s_waitcnt lgkmcnt(0)
	s_barrier
	s_setprio 1
	s_waitcnt lgkmcnt(0)
	v_mfma_f32_16x16x32_bf16 v[28:31], v[128:131], v[160:163], v[28:31]
	v_mfma_f32_16x16x32_bf16 v[24:27], v[136:139], v[160:163], v[24:27]
	v_mfma_f32_16x16x32_bf16 v[20:23], v[128:131], v[168:171], v[20:23]
	v_mfma_f32_16x16x32_bf16 v[16:19], v[136:139], v[168:171], v[16:19]
	v_mfma_f32_16x16x32_bf16 v[12:15], v[128:131], v[176:179], v[12:15]
	v_mfma_f32_16x16x32_bf16 v[8:11], v[136:139], v[176:179], v[8:11]
	v_mfma_f32_16x16x32_bf16 v[4:7], v[128:131], v[184:187], v[4:7]
	v_mfma_f32_16x16x32_bf16 v[0:3], v[136:139], v[184:187], v[0:3]
	v_mfma_f32_16x16x32_bf16 v[28:31], v[132:135], v[164:167], v[28:31]
	v_mfma_f32_16x16x32_bf16 v[24:27], v[140:143], v[164:167], v[24:27]
	v_mfma_f32_16x16x32_bf16 v[20:23], v[132:135], v[172:175], v[20:23]
	v_mfma_f32_16x16x32_bf16 v[16:19], v[140:143], v[172:175], v[16:19]
	v_mfma_f32_16x16x32_bf16 v[12:15], v[132:135], v[180:183], v[12:15]
	v_mfma_f32_16x16x32_bf16 v[8:11], v[140:143], v[180:183], v[8:11]
	v_mfma_f32_16x16x32_bf16 v[4:7], v[132:135], v[188:191], v[4:7]
	v_mfma_f32_16x16x32_bf16 v[0:3], v[140:143], v[188:191], v[0:3]
	s_setprio 0
	s_setprio 1
	v_mfma_f32_16x16x32_bf16 v[92:95], v[144:147], v[160:163], v[92:95]
	v_mfma_f32_16x16x32_bf16 v[88:91], v[152:155], v[160:163], v[88:91]
	v_mfma_f32_16x16x32_bf16 v[84:87], v[144:147], v[168:171], v[84:87]
	v_mfma_f32_16x16x32_bf16 v[80:83], v[152:155], v[168:171], v[80:83]
	v_mfma_f32_16x16x32_bf16 v[72:75], v[144:147], v[176:179], v[72:75]
	v_mfma_f32_16x16x32_bf16 v[64:67], v[152:155], v[176:179], v[64:67]
	v_mfma_f32_16x16x32_bf16 v[36:39], v[144:147], v[184:187], v[36:39]
	v_mfma_f32_16x16x32_bf16 v[32:35], v[152:155], v[184:187], v[32:35]
	v_mfma_f32_16x16x32_bf16 v[92:95], v[148:151], v[164:167], v[92:95]
	v_mfma_f32_16x16x32_bf16 v[88:91], v[156:159], v[164:167], v[88:91]
	v_mfma_f32_16x16x32_bf16 v[84:87], v[148:151], v[172:175], v[84:87]
	v_mfma_f32_16x16x32_bf16 v[80:83], v[156:159], v[172:175], v[80:83]
	v_mfma_f32_16x16x32_bf16 v[72:75], v[148:151], v[180:183], v[72:75]
	v_mfma_f32_16x16x32_bf16 v[64:67], v[156:159], v[180:183], v[64:67]
	v_mfma_f32_16x16x32_bf16 v[36:39], v[148:151], v[188:191], v[36:39]
	v_mfma_f32_16x16x32_bf16 v[32:35], v[156:159], v[188:191], v[32:35]
	s_setprio 0
	s_barrier
	s_add_i32 vcc_hi, 0, 0x18000
	s_add_i32 s18, 0, 0x1c000
	v_add_u32_e32 v140, vcc_hi, v209
	v_add_u32_e32 v156, s18, v209
	ds_read_b128 v[128:131], v140
	ds_read_b128 v[132:135], v140 offset:1024
	ds_read_b128 v[136:139], v140 offset:2048
	ds_read_b128 v[140:143], v140 offset:3072
	ds_read_b128 v[144:147], v156
	ds_read_b128 v[148:151], v156 offset:1024
	ds_read_b128 v[152:155], v156 offset:2048
	ds_read_b128 v[156:159], v156 offset:3072
	s_add_u32 s20, s56, 0x40000
	s_addc_u32 s21, s57, 0
	s_mov_b32 m0, s62
	v_lshl_add_u64 v[230:231], s[20:21], 0, v[192:193]
	ds_read_b128 v[160:163], v227 offset:32768
	ds_read_b128 v[164:167], v227 offset:33792
	ds_read_b128 v[168:171], v227 offset:34816
	ds_read_b128 v[172:175], v227 offset:35840
	ds_read_b128 v[176:179], v227 offset:36864
	ds_read_b128 v[180:183], v227 offset:37888
	ds_read_b128 v[184:187], v227 offset:38912
	ds_read_b128 v[188:191], v227 offset:39936
	global_load_lds_dwordx4 v[230:231], off
	v_lshl_add_u64 v[230:231], s[20:21], 0, v[196:197]
	s_mov_b32 m0, s63
	s_nop 0
	global_load_lds_dwordx4 v[230:231], off
	s_waitcnt vmcnt(8)
	s_waitcnt lgkmcnt(0)
	s_barrier
	s_setprio 1
	s_waitcnt lgkmcnt(0)
	v_mfma_f32_16x16x32_bf16 v[76:79], v[128:131], v[160:163], v[76:79]
	v_mfma_f32_16x16x32_bf16 v[68:71], v[136:139], v[160:163], v[68:71]
	v_mfma_f32_16x16x32_bf16 v[60:63], v[128:131], v[168:171], v[60:63]
	v_mfma_f32_16x16x32_bf16 v[56:59], v[136:139], v[168:171], v[56:59]
	v_mfma_f32_16x16x32_bf16 v[52:55], v[128:131], v[176:179], v[52:55]
	v_mfma_f32_16x16x32_bf16 v[48:51], v[136:139], v[176:179], v[48:51]
	v_mfma_f32_16x16x32_bf16 v[44:47], v[128:131], v[184:187], v[44:47]
	v_mfma_f32_16x16x32_bf16 v[40:43], v[136:139], v[184:187], v[40:43]
	v_mfma_f32_16x16x32_bf16 v[76:79], v[132:135], v[164:167], v[76:79]
	v_mfma_f32_16x16x32_bf16 v[68:71], v[140:143], v[164:167], v[68:71]
	v_mfma_f32_16x16x32_bf16 v[60:63], v[132:135], v[172:175], v[60:63]
	v_mfma_f32_16x16x32_bf16 v[56:59], v[140:143], v[172:175], v[56:59]
	v_mfma_f32_16x16x32_bf16 v[52:55], v[132:135], v[180:183], v[52:55]
	v_mfma_f32_16x16x32_bf16 v[48:51], v[140:143], v[180:183], v[48:51]
	v_mfma_f32_16x16x32_bf16 v[44:47], v[132:135], v[188:191], v[44:47]
	v_mfma_f32_16x16x32_bf16 v[40:43], v[140:143], v[188:191], v[40:43]
	s_setprio 0
	s_setprio 1
	v_mfma_f32_16x16x32_bf16 v[124:127], v[144:147], v[160:163], v[124:127]
	v_mfma_f32_16x16x32_bf16 v[120:123], v[152:155], v[160:163], v[120:123]
	v_mfma_f32_16x16x32_bf16 v[116:119], v[144:147], v[168:171], v[116:119]
	v_mfma_f32_16x16x32_bf16 v[112:115], v[152:155], v[168:171], v[112:115]
	v_mfma_f32_16x16x32_bf16 v[108:111], v[144:147], v[176:179], v[108:111]
	v_mfma_f32_16x16x32_bf16 v[104:107], v[152:155], v[176:179], v[104:107]
	v_mfma_f32_16x16x32_bf16 v[100:103], v[144:147], v[184:187], v[100:103]
	v_mfma_f32_16x16x32_bf16 v[96:99], v[152:155], v[184:187], v[96:99]
	v_mfma_f32_16x16x32_bf16 v[124:127], v[148:151], v[164:167], v[124:127]
	v_mfma_f32_16x16x32_bf16 v[120:123], v[156:159], v[164:167], v[120:123]
	v_mfma_f32_16x16x32_bf16 v[116:119], v[148:151], v[172:175], v[116:119]
	v_mfma_f32_16x16x32_bf16 v[112:115], v[156:159], v[172:175], v[112:115]
	v_mfma_f32_16x16x32_bf16 v[108:111], v[148:151], v[180:183], v[108:111]
	v_mfma_f32_16x16x32_bf16 v[104:107], v[156:159], v[180:183], v[104:107]
	v_mfma_f32_16x16x32_bf16 v[100:103], v[148:151], v[188:191], v[100:103]
	v_mfma_f32_16x16x32_bf16 v[96:99], v[156:159], v[188:191], v[96:99]
	s_setprio 0
	s_barrier
	s_add_i32 s19, vcc_hi, s3
	v_lshl_add_u64 v[216:217], v[216:217], 0, s[26:27]
	s_mov_b32 m0, s19
	ds_read_b128 v[160:163], v227 offset:49152
	ds_read_b128 v[164:167], v227 offset:50176
	ds_read_b128 v[168:171], v227 offset:51200
	ds_read_b128 v[172:175], v227 offset:52224
	ds_read_b128 v[176:179], v227 offset:53248
	ds_read_b128 v[180:183], v227 offset:54272
	ds_read_b128 v[184:187], v227 offset:55296
	ds_read_b128 v[188:191], v227 offset:56320
	global_load_lds_dwordx4 v[216:217], off
	s_add_i32 m0, s19, 0x2000
	s_add_u32 s20, s54, 0x40080
	v_lshl_add_u64 v[216:217], v[218:219], 0, s[26:27]
	s_addc_u32 s21, s55, 0
	s_add_i32 s18, s18, s3
	global_load_lds_dwordx4 v[216:217], off
	v_lshl_add_u64 v[216:217], s[20:21], 0, v[194:195]
	s_mov_b32 m0, s18
	s_nop 0
	global_load_lds_dwordx4 v[216:217], off
	v_lshl_add_u64 v[216:217], s[20:21], 0, v[198:199]
	s_add_i32 m0, s18, 0x2000
	s_nop 0
	global_load_lds_dwordx4 v[216:217], off
	v_lshl_add_u64 v[216:217], v[220:221], 0, s[26:27]
	s_mov_b32 m0, s68
	s_nop 0
	global_load_lds_dwordx4 v[216:217], off
	v_lshl_add_u64 v[216:217], v[222:223], 0, s[26:27]
	s_mov_b32 m0, s69
	s_nop 0
	global_load_lds_dwordx4 v[216:217], off
	s_waitcnt vmcnt(8)
	s_waitcnt lgkmcnt(0)
	s_barrier
	s_setprio 1
	s_waitcnt lgkmcnt(0)
	v_mfma_f32_16x16x32_bf16 v[28:31], v[128:131], v[160:163], v[28:31]
	v_mfma_f32_16x16x32_bf16 v[24:27], v[136:139], v[160:163], v[24:27]
	v_mfma_f32_16x16x32_bf16 v[20:23], v[128:131], v[168:171], v[20:23]
	v_mfma_f32_16x16x32_bf16 v[16:19], v[136:139], v[168:171], v[16:19]
	v_mfma_f32_16x16x32_bf16 v[12:15], v[128:131], v[176:179], v[12:15]
	v_mfma_f32_16x16x32_bf16 v[8:11], v[136:139], v[176:179], v[8:11]
	v_mfma_f32_16x16x32_bf16 v[4:7], v[128:131], v[184:187], v[4:7]
	v_mfma_f32_16x16x32_bf16 v[0:3], v[136:139], v[184:187], v[0:3]
	v_mfma_f32_16x16x32_bf16 v[28:31], v[132:135], v[164:167], v[28:31]
	v_mfma_f32_16x16x32_bf16 v[24:27], v[140:143], v[164:167], v[24:27]
	v_mfma_f32_16x16x32_bf16 v[20:23], v[132:135], v[172:175], v[20:23]
	v_mfma_f32_16x16x32_bf16 v[16:19], v[140:143], v[172:175], v[16:19]
	v_mfma_f32_16x16x32_bf16 v[12:15], v[132:135], v[180:183], v[12:15]
	v_mfma_f32_16x16x32_bf16 v[8:11], v[140:143], v[180:183], v[8:11]
	v_mfma_f32_16x16x32_bf16 v[4:7], v[132:135], v[188:191], v[4:7]
	v_mfma_f32_16x16x32_bf16 v[0:3], v[140:143], v[188:191], v[0:3]
	s_setprio 0
	s_setprio 1
	v_mfma_f32_16x16x32_bf16 v[92:95], v[144:147], v[160:163], v[92:95]
	v_mfma_f32_16x16x32_bf16 v[88:91], v[152:155], v[160:163], v[88:91]
	v_mfma_f32_16x16x32_bf16 v[84:87], v[144:147], v[168:171], v[84:87]
	v_mfma_f32_16x16x32_bf16 v[80:83], v[152:155], v[168:171], v[80:83]
	v_mfma_f32_16x16x32_bf16 v[72:75], v[144:147], v[176:179], v[72:75]
	v_mfma_f32_16x16x32_bf16 v[64:67], v[152:155], v[176:179], v[64:67]
	v_mfma_f32_16x16x32_bf16 v[36:39], v[144:147], v[184:187], v[36:39]
	v_mfma_f32_16x16x32_bf16 v[32:35], v[152:155], v[184:187], v[32:35]
	v_mfma_f32_16x16x32_bf16 v[92:95], v[148:151], v[164:167], v[92:95]
	v_mfma_f32_16x16x32_bf16 v[88:91], v[156:159], v[164:167], v[88:91]
	v_mfma_f32_16x16x32_bf16 v[84:87], v[148:151], v[172:175], v[84:87]
	v_mfma_f32_16x16x32_bf16 v[80:83], v[156:159], v[172:175], v[80:83]
	v_mfma_f32_16x16x32_bf16 v[72:75], v[148:151], v[180:183], v[72:75]
	v_mfma_f32_16x16x32_bf16 v[64:67], v[156:159], v[180:183], v[64:67]
	v_mfma_f32_16x16x32_bf16 v[36:39], v[148:151], v[188:191], v[36:39]
	v_mfma_f32_16x16x32_bf16 v[32:35], v[156:159], v[188:191], v[32:35]
	s_setprio 0
	s_add_i32 vcc_lo, vcc_lo, 2
	s_add_u32 s52, s52, 0x100
	s_addc_u32 s53, s53, 0
	s_add_u32 s96, s96, 0x100
	s_addc_u32 s97, s97, 0
	s_cmp_gt_u32 vcc_lo, 13
	s_cbranch_scc0 .Lrot0_head
	s_barrier
	s_and_b64 vcc, exec, s[28:29]
	s_cbranch_vccnz .LBB0_271
	v_lshl_add_u32 v216, s50, 8, v203
	s_cmp_lg_u32 s48, 32
	s_mov_b64 s[50:51], -1
	s_cbranch_scc1 .LBB0_272

.LBB0_510:
	s_andn2_b64 vcc, exec, s[4:5]
	s_cbranch_vccz .LBB0_520
	s_branch .LBB0_511

.LBB0_517:
	v_cndmask_b32_e64 v231, v234, v231, s[4:5]
	v_mul_f32_e32 v192, 0xbe0293ee, v231
	v_fmamk_f32 v144, v144, 0x3e0293ee, v192
	v_fmamk_f32 v145, v145, 0x3e0293ee, v192
	v_fmamk_f32 v146, v146, 0x3e0293ee, v192
	v_fmamk_f32 v147, v147, 0x3e0293ee, v192
	v_fmamk_f32 v148, v148, 0x3e0293ee, v192
	v_fmamk_f32 v149, v149, 0x3e0293ee, v192
	v_fmamk_f32 v150, v150, 0x3e0293ee, v192
	v_fmamk_f32 v151, v151, 0x3e0293ee, v192
	v_fmamk_f32 v152, v152, 0x3e0293ee, v192
	v_fmamk_f32 v153, v153, 0x3e0293ee, v192
	v_fmamk_f32 v154, v154, 0x3e0293ee, v192
	v_fmamk_f32 v155, v155, 0x3e0293ee, v192
	v_fmamk_f32 v156, v156, 0x3e0293ee, v192
	v_fmamk_f32 v157, v157, 0x3e0293ee, v192
	v_fmamk_f32 v158, v158, 0x3e0293ee, v192
	v_fmamk_f32 v159, v159, 0x3e0293ee, v192
	v_fmamk_f32 v128, v128, 0x3e0293ee, v192
	v_fmamk_f32 v129, v129, 0x3e0293ee, v192
	v_fmamk_f32 v130, v130, 0x3e0293ee, v192
	v_fmamk_f32 v131, v131, 0x3e0293ee, v192
	v_fmamk_f32 v132, v132, 0x3e0293ee, v192
	v_fmamk_f32 v133, v133, 0x3e0293ee, v192
	v_fmamk_f32 v134, v134, 0x3e0293ee, v192
	v_fmamk_f32 v135, v135, 0x3e0293ee, v192
	v_fmamk_f32 v136, v136, 0x3e0293ee, v192
	v_fmamk_f32 v137, v137, 0x3e0293ee, v192
	v_fmamk_f32 v138, v138, 0x3e0293ee, v192
	v_fmamk_f32 v139, v139, 0x3e0293ee, v192
	v_fmamk_f32 v140, v140, 0x3e0293ee, v192
	v_fmamk_f32 v141, v141, 0x3e0293ee, v192
	v_fmamk_f32 v142, v142, 0x3e0293ee, v192
	v_fmac_f32_e32 v192, 0x3e0293ee, v143
	v_exp_f32_e32 v143, v144
	v_exp_f32_e32 v145, v145
	v_exp_f32_e32 v146, v146
	v_exp_f32_e32 v147, v147
	v_exp_f32_e32 v148, v148
	v_exp_f32_e32 v193, v128
	v_exp_f32_e32 v149, v149
	v_add_f32_e32 v128, v145, v143
	v_exp_f32_e32 v150, v150
	v_add_f32_e32 v128, v146, v128
	v_exp_f32_e32 v151, v151
	v_add_f32_e32 v128, v147, v128
	v_exp_f32_e32 v152, v152
	v_add_f32_e32 v128, v148, v128
	v_exp_f32_e32 v153, v153
	v_add_f32_e32 v128, v149, v128
	v_exp_f32_e32 v154, v154
	v_add_f32_e32 v128, v150, v128
	v_exp_f32_e32 v155, v155
	v_add_f32_e32 v128, v151, v128
	v_exp_f32_e32 v156, v156
	v_add_f32_e32 v128, v152, v128
	v_exp_f32_e32 v157, v157
	v_add_f32_e32 v128, v153, v128
	v_exp_f32_e32 v158, v158
	v_add_f32_e32 v128, v154, v128
	v_exp_f32_e32 v159, v159
	v_add_f32_e32 v128, v155, v128
	v_add_f32_e32 v128, v156, v128
	v_exp_f32_e32 v194, v129
	v_add_f32_e32 v128, v157, v128
	v_exp_f32_e32 v195, v130
	v_add_f32_e32 v128, v158, v128
	v_exp_f32_e32 v196, v131
	v_add_f32_e32 v128, v159, v128
	v_exp_f32_e32 v197, v132
	v_add_f32_e32 v128, v193, v128
	v_exp_f32_e32 v198, v133
	v_add_f32_e32 v128, v194, v128
	v_exp_f32_e32 v199, v134
	v_add_f32_e32 v128, v195, v128
	v_exp_f32_e32 v135, v135
	v_add_f32_e32 v128, v196, v128
	v_exp_f32_e32 v200, v136
	v_add_f32_e32 v128, v197, v128
	v_exp_f32_e32 v201, v137
	v_add_f32_e32 v128, v198, v128
	v_exp_f32_e32 v202, v138
	v_add_f32_e32 v128, v199, v128
	v_exp_f32_e32 v203, v139
	v_add_f32_e32 v128, v135, v128
	v_exp_f32_e32 v204, v140
	v_add_f32_e32 v128, v200, v128
	v_exp_f32_e32 v205, v141
	v_add_f32_e32 v128, v201, v128
	v_exp_f32_e32 v206, v142
	v_add_f32_e32 v128, v202, v128
	v_exp_f32_e32 v192, v192
	v_add_f32_e32 v128, v203, v128
	v_add_f32_e32 v128, v204, v128
	v_add_f32_e32 v128, v205, v128
	v_add_f32_e32 v128, v206, v128
	v_add_f32_e32 v128, v192, v128
	v_mov_b32_e32 v129, v128
	s_nop 1
	v_permlane32_swap_b32_e32 v128, v129
	v_add_f32_e32 v144, v128, v129
	v_fmac_f32_e32 v144, v232, v233
	v_cvt_pk_bf16_f32 v128, v143, v145
	v_cvt_pk_bf16_f32 v129, v146, v147
	v_cvt_pk_bf16_f32 v130, v148, v149
	v_cvt_pk_bf16_f32 v131, v150, v151
	v_cvt_pk_bf16_f32 v136, v152, v153
	v_cvt_pk_bf16_f32 v137, v154, v155
	v_cvt_pk_bf16_f32 v138, v156, v157
	v_cvt_pk_bf16_f32 v139, v158, v159
	v_cvt_pk_bf16_f32 v132, v193, v194
	v_cvt_pk_bf16_f32 v133, v195, v196
	v_cvt_pk_bf16_f32 v134, v197, v198
	v_cvt_pk_bf16_f32 v135, v199, v135
	v_cvt_pk_bf16_f32 v140, v200, v201
	v_cvt_pk_bf16_f32 v141, v202, v203
	v_cvt_pk_bf16_f32 v142, v204, v205
	v_cvt_pk_bf16_f32 v143, v206, v192
	v_lshl_add_u32 v145, s76, 15, v230
	ds_read_b64_tr_b16 v[146:147], v145 offset:0
	ds_read_b64_tr_b16 v[148:149], v145 offset:4096
	ds_read_b64_tr_b16 v[150:151], v145 offset:512
	ds_read_b64_tr_b16 v[152:153], v145 offset:4608
	ds_read_b64_tr_b16 v[154:155], v145 offset:1024
	ds_read_b64_tr_b16 v[156:157], v145 offset:5120
	ds_read_b64_tr_b16 v[192:193], v145 offset:1536
	ds_read_b64_tr_b16 v[194:195], v145 offset:5632
	ds_read_b64_tr_b16 v[196:197], v145 offset:2048
	ds_read_b64_tr_b16 v[198:199], v145 offset:6144
	ds_read_b64_tr_b16 v[200:201], v145 offset:2560
	ds_read_b64_tr_b16 v[202:203], v145 offset:6656
	ds_read_b64_tr_b16 v[204:205], v145 offset:3072
	ds_read_b64_tr_b16 v[206:207], v145 offset:7168
	s_waitcnt lgkmcnt(12)
	s_nop 0
	v_mfma_f32_32x32x16_bf16 v[0:15], v[128:131], v[146:149], v[0:15]
	ds_read_b64_tr_b16 v[232:233], v145 offset:3584
	ds_read_b64_tr_b16 v[234:235], v145 offset:7680
	s_waitcnt lgkmcnt(12)
	v_mfma_f32_32x32x16_bf16 v[112:127], v[128:131], v[150:153], v[112:127]
	ds_read_b64_tr_b16 v[146:147], v145 offset:8192
	ds_read_b64_tr_b16 v[148:149], v145 offset:12288
	s_waitcnt lgkmcnt(12)
	v_mfma_f32_32x32x16_bf16 v[96:111], v[128:131], v[154:157], v[96:111]
	ds_read_b64_tr_b16 v[150:151], v145 offset:8704
	ds_read_b64_tr_b16 v[152:153], v145 offset:12800
	s_waitcnt lgkmcnt(12)
	v_mfma_f32_32x32x16_bf16 v[80:95], v[128:131], v[192:195], v[80:95]
	ds_read_b64_tr_b16 v[154:155], v145 offset:9216
	ds_read_b64_tr_b16 v[156:157], v145 offset:13312
	s_waitcnt lgkmcnt(12)
	v_mfma_f32_32x32x16_bf16 v[64:79], v[128:131], v[196:199], v[64:79]
	ds_read_b64_tr_b16 v[192:193], v145 offset:9728
	ds_read_b64_tr_b16 v[194:195], v145 offset:13824
	s_waitcnt lgkmcnt(12)
	v_mfma_f32_32x32x16_bf16 v[48:63], v[128:131], v[200:203], v[48:63]
	ds_read_b64_tr_b16 v[196:197], v145 offset:10240
	ds_read_b64_tr_b16 v[198:199], v145 offset:14336
	s_waitcnt lgkmcnt(12)
	v_mfma_f32_32x32x16_bf16 v[32:47], v[128:131], v[204:207], v[32:47]
	ds_read_b64_tr_b16 v[200:201], v145 offset:10752
	ds_read_b64_tr_b16 v[202:203], v145 offset:14848
	s_waitcnt lgkmcnt(12)
	v_mfma_f32_32x32x16_bf16 v[16:31], v[128:131], v[232:235], v[16:31]
	ds_read_b64_tr_b16 v[204:205], v145 offset:11264
	ds_read_b64_tr_b16 v[206:207], v145 offset:15360
	s_waitcnt lgkmcnt(12)
	v_mfma_f32_32x32x16_bf16 v[0:15], v[136:139], v[146:149], v[0:15]
	ds_read_b64_tr_b16 v[232:233], v145 offset:11776
	ds_read_b64_tr_b16 v[234:235], v145 offset:15872
	s_waitcnt lgkmcnt(12)
	v_mfma_f32_32x32x16_bf16 v[112:127], v[136:139], v[150:153], v[112:127]
	ds_read_b64_tr_b16 v[146:147], v145 offset:16384
	ds_read_b64_tr_b16 v[148:149], v145 offset:20480
	s_waitcnt lgkmcnt(12)
	v_mfma_f32_32x32x16_bf16 v[96:111], v[136:139], v[154:157], v[96:111]
	ds_read_b64_tr_b16 v[150:151], v145 offset:16896
	ds_read_b64_tr_b16 v[152:153], v145 offset:20992
	s_waitcnt lgkmcnt(12)
	v_mfma_f32_32x32x16_bf16 v[80:95], v[136:139], v[192:195], v[80:95]
	ds_read_b64_tr_b16 v[154:155], v145 offset:17408
	ds_read_b64_tr_b16 v[156:157], v145 offset:21504
	s_waitcnt lgkmcnt(12)
	v_mfma_f32_32x32x16_bf16 v[64:79], v[136:139], v[196:199], v[64:79]
	ds_read_b64_tr_b16 v[192:193], v145 offset:17920
	ds_read_b64_tr_b16 v[194:195], v145 offset:22016
	s_waitcnt lgkmcnt(12)
	v_mfma_f32_32x32x16_bf16 v[48:63], v[136:139], v[200:203], v[48:63]
	ds_read_b64_tr_b16 v[196:197], v145 offset:18432
	ds_read_b64_tr_b16 v[198:199], v145 offset:22528
	s_waitcnt lgkmcnt(12)
	v_mfma_f32_32x32x16_bf16 v[32:47], v[136:139], v[204:207], v[32:47]
	ds_read_b64_tr_b16 v[200:201], v145 offset:18944
	ds_read_b64_tr_b16 v[202:203], v145 offset:23040
	s_waitcnt lgkmcnt(12)
	v_mfma_f32_32x32x16_bf16 v[16:31], v[136:139], v[232:235], v[16:31]
	ds_read_b64_tr_b16 v[204:205], v145 offset:19456
	ds_read_b64_tr_b16 v[206:207], v145 offset:23552
	s_waitcnt lgkmcnt(12)
	v_mfma_f32_32x32x16_bf16 v[0:15], v[132:135], v[146:149], v[0:15]
	ds_read_b64_tr_b16 v[232:233], v145 offset:19968
	ds_read_b64_tr_b16 v[234:235], v145 offset:24064
	s_waitcnt lgkmcnt(12)
	v_mfma_f32_32x32x16_bf16 v[112:127], v[132:135], v[150:153], v[112:127]
	ds_read_b64_tr_b16 v[146:147], v145 offset:24576
	ds_read_b64_tr_b16 v[148:149], v145 offset:28672
	s_waitcnt lgkmcnt(12)
	v_mfma_f32_32x32x16_bf16 v[96:111], v[132:135], v[154:157], v[96:111]
	ds_read_b64_tr_b16 v[150:151], v145 offset:25088
	ds_read_b64_tr_b16 v[152:153], v145 offset:29184
	s_waitcnt lgkmcnt(12)
	v_mfma_f32_32x32x16_bf16 v[80:95], v[132:135], v[192:195], v[80:95]
	ds_read_b64_tr_b16 v[154:155], v145 offset:25600
	ds_read_b64_tr_b16 v[156:157], v145 offset:29696
	s_waitcnt lgkmcnt(12)
	v_mfma_f32_32x32x16_bf16 v[64:79], v[132:135], v[196:199], v[64:79]
	ds_read_b64_tr_b16 v[192:193], v145 offset:26112
	ds_read_b64_tr_b16 v[194:195], v145 offset:30208
	s_waitcnt lgkmcnt(12)
	v_mfma_f32_32x32x16_bf16 v[48:63], v[132:135], v[200:203], v[48:63]
	ds_read_b64_tr_b16 v[196:197], v145 offset:26624
	ds_read_b64_tr_b16 v[198:199], v145 offset:30720
	s_waitcnt lgkmcnt(12)
	v_mfma_f32_32x32x16_bf16 v[32:47], v[132:135], v[204:207], v[32:47]
	ds_read_b64_tr_b16 v[200:201], v145 offset:27136
	ds_read_b64_tr_b16 v[202:203], v145 offset:31232
	s_waitcnt lgkmcnt(12)
	v_mfma_f32_32x32x16_bf16 v[16:31], v[132:135], v[232:235], v[16:31]
	ds_read_b64_tr_b16 v[204:205], v145 offset:27648
	ds_read_b64_tr_b16 v[206:207], v145 offset:31744
	s_waitcnt lgkmcnt(12)
	v_mfma_f32_32x32x16_bf16 v[0:15], v[140:143], v[146:149], v[0:15]
	ds_read_b64_tr_b16 v[232:233], v145 offset:28160
	ds_read_b64_tr_b16 v[234:235], v145 offset:32256
	s_waitcnt lgkmcnt(12)
	v_mfma_f32_32x32x16_bf16 v[112:127], v[140:143], v[150:153], v[112:127]
	s_waitcnt lgkmcnt(10)
	v_mfma_f32_32x32x16_bf16 v[96:111], v[140:143], v[154:157], v[96:111]
	s_waitcnt lgkmcnt(8)
	v_mfma_f32_32x32x16_bf16 v[80:95], v[140:143], v[192:195], v[80:95]
	s_waitcnt lgkmcnt(6)
	v_mfma_f32_32x32x16_bf16 v[64:79], v[140:143], v[196:199], v[64:79]
	s_add_i32 s4, s76, 1
	s_cmp_lg_u32 s76, 2
	s_cselect_b32 s76, s4, 0
	s_add_i32 s4, s74, 1
	s_cmp_lg_u32 s74, 2
	s_cselect_b32 s74, s4, 0
	s_add_u32 s22, s22, 0x20000
	s_waitcnt lgkmcnt(4)
	v_mfma_f32_32x32x16_bf16 v[48:63], v[140:143], v[200:203], v[48:63]
	s_addc_u32 s23, s23, 0
	s_add_i32 s86, s86, 1
	s_cmp_eq_u32 s22, 0x800000
	s_waitcnt lgkmcnt(2)
	v_mfma_f32_32x32x16_bf16 v[32:47], v[140:143], v[204:207], v[32:47]
	s_waitcnt lgkmcnt(0)
	v_mfma_f32_32x32x16_bf16 v[16:31], v[140:143], v[232:235], v[16:31]
	s_cbranch_scc1 .LBB0_521
	v_mov_b32_e32 v232, v144
	s_cmp_eq_u32 s22, 0x7e0000
	s_mov_b64 s[4:5], -1
	s_cbranch_scc1 .LBB0_510
	s_branch .Lrota0_head

.LBB0_910:
	v_cndmask_b32_e64 v231, v234, v231, s[4:5]
	v_mul_f32_e32 v192, 0xbe0293ee, v231
	v_fmamk_f32 v144, v144, 0x3e0293ee, v192
	v_fmamk_f32 v145, v145, 0x3e0293ee, v192
	v_fmamk_f32 v146, v146, 0x3e0293ee, v192
	v_fmamk_f32 v147, v147, 0x3e0293ee, v192
	v_fmamk_f32 v148, v148, 0x3e0293ee, v192
	v_fmamk_f32 v149, v149, 0x3e0293ee, v192
	v_fmamk_f32 v150, v150, 0x3e0293ee, v192
	v_fmamk_f32 v151, v151, 0x3e0293ee, v192
	v_fmamk_f32 v152, v152, 0x3e0293ee, v192
	v_fmamk_f32 v153, v153, 0x3e0293ee, v192
	v_fmamk_f32 v154, v154, 0x3e0293ee, v192
	v_fmamk_f32 v155, v155, 0x3e0293ee, v192
	v_fmamk_f32 v156, v156, 0x3e0293ee, v192
	v_fmamk_f32 v157, v157, 0x3e0293ee, v192
	v_fmamk_f32 v158, v158, 0x3e0293ee, v192
	v_fmamk_f32 v159, v159, 0x3e0293ee, v192
	v_fmamk_f32 v128, v128, 0x3e0293ee, v192
	v_fmamk_f32 v129, v129, 0x3e0293ee, v192
	v_fmamk_f32 v130, v130, 0x3e0293ee, v192
	v_fmamk_f32 v131, v131, 0x3e0293ee, v192
	v_fmamk_f32 v132, v132, 0x3e0293ee, v192
	v_fmamk_f32 v133, v133, 0x3e0293ee, v192
	v_fmamk_f32 v134, v134, 0x3e0293ee, v192
	v_fmamk_f32 v135, v135, 0x3e0293ee, v192
	v_fmamk_f32 v136, v136, 0x3e0293ee, v192
	v_fmamk_f32 v137, v137, 0x3e0293ee, v192
	v_fmamk_f32 v138, v138, 0x3e0293ee, v192
	v_fmamk_f32 v139, v139, 0x3e0293ee, v192
	v_fmamk_f32 v140, v140, 0x3e0293ee, v192
	v_fmamk_f32 v141, v141, 0x3e0293ee, v192
	v_fmamk_f32 v142, v142, 0x3e0293ee, v192
	v_fmac_f32_e32 v192, 0x3e0293ee, v143
	v_exp_f32_e32 v143, v144
	v_exp_f32_e32 v145, v145
	v_exp_f32_e32 v146, v146
	v_exp_f32_e32 v147, v147
	v_exp_f32_e32 v148, v148
	v_exp_f32_e32 v193, v128
	v_exp_f32_e32 v149, v149
	v_add_f32_e32 v128, v145, v143
	v_exp_f32_e32 v150, v150
	v_add_f32_e32 v128, v146, v128
	v_exp_f32_e32 v151, v151
	v_add_f32_e32 v128, v147, v128
	v_exp_f32_e32 v152, v152
	v_add_f32_e32 v128, v148, v128
	v_exp_f32_e32 v153, v153
	v_add_f32_e32 v128, v149, v128
	v_exp_f32_e32 v154, v154
	v_add_f32_e32 v128, v150, v128
	v_exp_f32_e32 v155, v155
	v_add_f32_e32 v128, v151, v128
	v_exp_f32_e32 v156, v156
	v_add_f32_e32 v128, v152, v128
	v_exp_f32_e32 v157, v157
	v_add_f32_e32 v128, v153, v128
	v_exp_f32_e32 v158, v158
	v_add_f32_e32 v128, v154, v128
	v_exp_f32_e32 v159, v159
	v_add_f32_e32 v128, v155, v128
	v_add_f32_e32 v128, v156, v128
	v_exp_f32_e32 v194, v129
	v_add_f32_e32 v128, v157, v128
	v_exp_f32_e32 v195, v130
	v_add_f32_e32 v128, v158, v128
	v_exp_f32_e32 v196, v131
	v_add_f32_e32 v128, v159, v128
	v_exp_f32_e32 v197, v132
	v_add_f32_e32 v128, v193, v128
	v_exp_f32_e32 v198, v133
	v_add_f32_e32 v128, v194, v128
	v_exp_f32_e32 v199, v134
	v_add_f32_e32 v128, v195, v128
	v_exp_f32_e32 v135, v135
	v_add_f32_e32 v128, v196, v128
	v_exp_f32_e32 v200, v136
	v_add_f32_e32 v128, v197, v128
	v_exp_f32_e32 v201, v137
	v_add_f32_e32 v128, v198, v128
	v_exp_f32_e32 v202, v138
	v_add_f32_e32 v128, v199, v128
	v_exp_f32_e32 v203, v139
	v_add_f32_e32 v128, v135, v128
	v_exp_f32_e32 v204, v140
	v_add_f32_e32 v128, v200, v128
	v_exp_f32_e32 v205, v141
	v_add_f32_e32 v128, v201, v128
	v_exp_f32_e32 v206, v142
	v_add_f32_e32 v128, v202, v128
	v_exp_f32_e32 v192, v192
	v_add_f32_e32 v128, v203, v128
	v_add_f32_e32 v128, v204, v128
	v_add_f32_e32 v128, v205, v128
	v_add_f32_e32 v128, v206, v128
	v_add_f32_e32 v128, v192, v128
	v_mov_b32_e32 v129, v128
	s_nop 1
	v_permlane32_swap_b32_e32 v128, v129
	v_add_f32_e32 v144, v128, v129
	v_fmac_f32_e32 v144, v232, v233
	v_cvt_pk_bf16_f32 v128, v143, v145
	v_cvt_pk_bf16_f32 v129, v146, v147
	v_cvt_pk_bf16_f32 v130, v148, v149
	v_cvt_pk_bf16_f32 v131, v150, v151
	v_cvt_pk_bf16_f32 v136, v152, v153
	v_cvt_pk_bf16_f32 v137, v154, v155
	v_cvt_pk_bf16_f32 v138, v156, v157
	v_cvt_pk_bf16_f32 v139, v158, v159
	v_cvt_pk_bf16_f32 v132, v193, v194
	v_cvt_pk_bf16_f32 v133, v195, v196
	v_cvt_pk_bf16_f32 v134, v197, v198
	v_cvt_pk_bf16_f32 v135, v199, v135
	v_cvt_pk_bf16_f32 v140, v200, v201
	v_cvt_pk_bf16_f32 v141, v202, v203
	v_cvt_pk_bf16_f32 v142, v204, v205
	v_cvt_pk_bf16_f32 v143, v206, v192
	v_lshl_add_u32 v145, s80, 15, v230
	ds_read_b64_tr_b16 v[146:147], v145 offset:0
	ds_read_b64_tr_b16 v[148:149], v145 offset:4096
	ds_read_b64_tr_b16 v[150:151], v145 offset:512
	ds_read_b64_tr_b16 v[152:153], v145 offset:4608
	ds_read_b64_tr_b16 v[154:155], v145 offset:1024
	ds_read_b64_tr_b16 v[156:157], v145 offset:5120
	ds_read_b64_tr_b16 v[192:193], v145 offset:1536
	ds_read_b64_tr_b16 v[194:195], v145 offset:5632
	ds_read_b64_tr_b16 v[196:197], v145 offset:2048
	ds_read_b64_tr_b16 v[198:199], v145 offset:6144
	ds_read_b64_tr_b16 v[200:201], v145 offset:2560
	ds_read_b64_tr_b16 v[202:203], v145 offset:6656
	ds_read_b64_tr_b16 v[204:205], v145 offset:3072
	ds_read_b64_tr_b16 v[206:207], v145 offset:7168
	s_waitcnt lgkmcnt(12)
	s_nop 0
	v_mfma_f32_32x32x16_bf16 v[0:15], v[128:131], v[146:149], v[0:15]
	ds_read_b64_tr_b16 v[232:233], v145 offset:3584
	ds_read_b64_tr_b16 v[234:235], v145 offset:7680
	s_waitcnt lgkmcnt(12)
	v_mfma_f32_32x32x16_bf16 v[112:127], v[128:131], v[150:153], v[112:127]
	ds_read_b64_tr_b16 v[146:147], v145 offset:8192
	ds_read_b64_tr_b16 v[148:149], v145 offset:12288
	s_waitcnt lgkmcnt(12)
	v_mfma_f32_32x32x16_bf16 v[96:111], v[128:131], v[154:157], v[96:111]
	ds_read_b64_tr_b16 v[150:151], v145 offset:8704
	ds_read_b64_tr_b16 v[152:153], v145 offset:12800
	s_waitcnt lgkmcnt(12)
	v_mfma_f32_32x32x16_bf16 v[80:95], v[128:131], v[192:195], v[80:95]
	ds_read_b64_tr_b16 v[154:155], v145 offset:9216
	ds_read_b64_tr_b16 v[156:157], v145 offset:13312
	s_waitcnt lgkmcnt(12)
	v_mfma_f32_32x32x16_bf16 v[64:79], v[128:131], v[196:199], v[64:79]
	ds_read_b64_tr_b16 v[192:193], v145 offset:9728
	ds_read_b64_tr_b16 v[194:195], v145 offset:13824
	s_waitcnt lgkmcnt(12)
	v_mfma_f32_32x32x16_bf16 v[48:63], v[128:131], v[200:203], v[48:63]
	ds_read_b64_tr_b16 v[196:197], v145 offset:10240
	ds_read_b64_tr_b16 v[198:199], v145 offset:14336
	s_waitcnt lgkmcnt(12)
	v_mfma_f32_32x32x16_bf16 v[32:47], v[128:131], v[204:207], v[32:47]
	ds_read_b64_tr_b16 v[200:201], v145 offset:10752
	ds_read_b64_tr_b16 v[202:203], v145 offset:14848
	s_waitcnt lgkmcnt(12)
	v_mfma_f32_32x32x16_bf16 v[16:31], v[128:131], v[232:235], v[16:31]
	ds_read_b64_tr_b16 v[204:205], v145 offset:11264
	ds_read_b64_tr_b16 v[206:207], v145 offset:15360
	s_waitcnt lgkmcnt(12)
	v_mfma_f32_32x32x16_bf16 v[0:15], v[136:139], v[146:149], v[0:15]
	ds_read_b64_tr_b16 v[232:233], v145 offset:11776
	ds_read_b64_tr_b16 v[234:235], v145 offset:15872
	s_waitcnt lgkmcnt(12)
	v_mfma_f32_32x32x16_bf16 v[112:127], v[136:139], v[150:153], v[112:127]
	ds_read_b64_tr_b16 v[146:147], v145 offset:16384
	ds_read_b64_tr_b16 v[148:149], v145 offset:20480
	s_waitcnt lgkmcnt(12)
	v_mfma_f32_32x32x16_bf16 v[96:111], v[136:139], v[154:157], v[96:111]
	ds_read_b64_tr_b16 v[150:151], v145 offset:16896
	ds_read_b64_tr_b16 v[152:153], v145 offset:20992
	s_waitcnt lgkmcnt(12)
	v_mfma_f32_32x32x16_bf16 v[80:95], v[136:139], v[192:195], v[80:95]
	ds_read_b64_tr_b16 v[154:155], v145 offset:17408
	ds_read_b64_tr_b16 v[156:157], v145 offset:21504
	s_waitcnt lgkmcnt(12)
	v_mfma_f32_32x32x16_bf16 v[64:79], v[136:139], v[196:199], v[64:79]
	ds_read_b64_tr_b16 v[192:193], v145 offset:17920
	ds_read_b64_tr_b16 v[194:195], v145 offset:22016
	s_waitcnt lgkmcnt(12)
	v_mfma_f32_32x32x16_bf16 v[48:63], v[136:139], v[200:203], v[48:63]
	ds_read_b64_tr_b16 v[196:197], v145 offset:18432
	ds_read_b64_tr_b16 v[198:199], v145 offset:22528
	s_waitcnt lgkmcnt(12)
	v_mfma_f32_32x32x16_bf16 v[32:47], v[136:139], v[204:207], v[32:47]
	ds_read_b64_tr_b16 v[200:201], v145 offset:18944
	ds_read_b64_tr_b16 v[202:203], v145 offset:23040
	s_waitcnt lgkmcnt(12)
	v_mfma_f32_32x32x16_bf16 v[16:31], v[136:139], v[232:235], v[16:31]
	ds_read_b64_tr_b16 v[204:205], v145 offset:19456
	ds_read_b64_tr_b16 v[206:207], v145 offset:23552
	s_waitcnt lgkmcnt(12)
	v_mfma_f32_32x32x16_bf16 v[0:15], v[132:135], v[146:149], v[0:15]
	ds_read_b64_tr_b16 v[232:233], v145 offset:19968
	ds_read_b64_tr_b16 v[234:235], v145 offset:24064
	s_waitcnt lgkmcnt(12)
	v_mfma_f32_32x32x16_bf16 v[112:127], v[132:135], v[150:153], v[112:127]
	ds_read_b64_tr_b16 v[146:147], v145 offset:24576
	ds_read_b64_tr_b16 v[148:149], v145 offset:28672
	s_waitcnt lgkmcnt(12)
	v_mfma_f32_32x32x16_bf16 v[96:111], v[132:135], v[154:157], v[96:111]
	ds_read_b64_tr_b16 v[150:151], v145 offset:25088
	ds_read_b64_tr_b16 v[152:153], v145 offset:29184
	s_waitcnt lgkmcnt(12)
	v_mfma_f32_32x32x16_bf16 v[80:95], v[132:135], v[192:195], v[80:95]
	ds_read_b64_tr_b16 v[154:155], v145 offset:25600
	ds_read_b64_tr_b16 v[156:157], v145 offset:29696
	s_waitcnt lgkmcnt(12)
	v_mfma_f32_32x32x16_bf16 v[64:79], v[132:135], v[196:199], v[64:79]
	ds_read_b64_tr_b16 v[192:193], v145 offset:26112
	ds_read_b64_tr_b16 v[194:195], v145 offset:30208
	s_waitcnt lgkmcnt(12)
	v_mfma_f32_32x32x16_bf16 v[48:63], v[132:135], v[200:203], v[48:63]
	ds_read_b64_tr_b16 v[196:197], v145 offset:26624
	ds_read_b64_tr_b16 v[198:199], v145 offset:30720
	s_waitcnt lgkmcnt(12)
	v_mfma_f32_32x32x16_bf16 v[32:47], v[132:135], v[204:207], v[32:47]
	ds_read_b64_tr_b16 v[200:201], v145 offset:27136
	ds_read_b64_tr_b16 v[202:203], v145 offset:31232
	s_waitcnt lgkmcnt(12)
	v_mfma_f32_32x32x16_bf16 v[16:31], v[132:135], v[232:235], v[16:31]
	ds_read_b64_tr_b16 v[204:205], v145 offset:27648
	ds_read_b64_tr_b16 v[206:207], v145 offset:31744
	s_waitcnt lgkmcnt(12)
	v_mfma_f32_32x32x16_bf16 v[0:15], v[140:143], v[146:149], v[0:15]
	ds_read_b64_tr_b16 v[232:233], v145 offset:28160
	ds_read_b64_tr_b16 v[234:235], v145 offset:32256
	s_waitcnt lgkmcnt(12)
	v_mfma_f32_32x32x16_bf16 v[112:127], v[140:143], v[150:153], v[112:127]
	s_waitcnt lgkmcnt(10)
	v_mfma_f32_32x32x16_bf16 v[96:111], v[140:143], v[154:157], v[96:111]
	s_waitcnt lgkmcnt(8)
	v_mfma_f32_32x32x16_bf16 v[80:95], v[140:143], v[192:195], v[80:95]
	s_waitcnt lgkmcnt(6)
	v_mfma_f32_32x32x16_bf16 v[64:79], v[140:143], v[196:199], v[64:79]
	s_add_i32 s4, s80, 1
	s_cmp_lg_u32 s80, 2
	s_cselect_b32 s80, s4, 0
	s_add_i32 s4, s78, 1
	s_cmp_lg_u32 s78, 2
	s_cselect_b32 s78, s4, 0
	s_add_u32 s22, s22, 0x20000
	s_waitcnt lgkmcnt(4)
	v_mfma_f32_32x32x16_bf16 v[48:63], v[140:143], v[200:203], v[48:63]
	s_addc_u32 s23, s23, 0
	s_add_i32 s86, s86, 1
	s_cmp_eq_u32 s22, 0x800000
	s_waitcnt lgkmcnt(2)
	v_mfma_f32_32x32x16_bf16 v[32:47], v[140:143], v[204:207], v[32:47]
	s_waitcnt lgkmcnt(0)
	v_mfma_f32_32x32x16_bf16 v[16:31], v[140:143], v[232:235], v[16:31]
	s_cbranch_scc1 .LBB0_914
	v_mov_b32_e32 v232, v144
	s_cmp_eq_u32 s22, 0x7e0000
	s_mov_b64 s[4:5], -1
	s_cbranch_scc1 .LBB0_903
	s_branch .Lrota1_head

.LBB0_1045:
	s_ashr_i32 s21, s20, 31
	s_lshl_b64 s[22:23], s[20:21], 19
	s_add_u32 s22, s3, s22
	s_addc_u32 s23, s33, s23
	s_and_b64 s[24:25], s[4:5], exec
	s_cselect_b32 s21, s23, s31
	s_cselect_b32 s27, s22, s30
	s_ashr_i32 s19, s18, 31
	s_lshl_b64 s[24:25], s[18:19], 19
	s_add_u32 s24, s38, s24
	s_addc_u32 s25, s39, s25
	s_and_b64 s[36:37], s[4:5], exec
	s_cselect_b32 s19, s25, s35
	s_cselect_b32 s52, s24, s34
	s_add_u32 s30, s30, 0x40080
	s_addc_u32 s31, s31, 0
	s_add_u32 s53, s34, 0x100
	v_mov_b32_e32 v0, 0
	s_addc_u32 s54, s35, 0
	s_mov_b32 s55, -2
	s_waitcnt lgkmcnt(0)
	v_mov_b32_e32 v1, v0
	v_mov_b32_e32 v2, v0
	v_mov_b32_e32 v3, v0
	v_mov_b32_e32 v4, v0
	v_mov_b32_e32 v5, v0
	v_mov_b32_e32 v6, v0
	v_mov_b32_e32 v7, v0
	v_mov_b32_e32 v16, v0
	v_mov_b32_e32 v17, v0
	v_mov_b32_e32 v18, v0
	v_mov_b32_e32 v19, v0
	v_mov_b32_e32 v20, v0
	v_mov_b32_e32 v21, v0
	v_mov_b32_e32 v22, v0
	v_mov_b32_e32 v23, v0
	v_mov_b32_e32 v32, v0
	v_mov_b32_e32 v33, v0
	v_mov_b32_e32 v34, v0
	v_mov_b32_e32 v35, v0
	v_mov_b32_e32 v36, v0
	v_mov_b32_e32 v37, v0
	v_mov_b32_e32 v38, v0
	v_mov_b32_e32 v39, v0
	v_mov_b32_e32 v48, v0
	v_mov_b32_e32 v49, v0
	v_mov_b32_e32 v50, v0
	v_mov_b32_e32 v51, v0
	v_mov_b32_e32 v52, v0
	v_mov_b32_e32 v53, v0
	v_mov_b32_e32 v54, v0
	v_mov_b32_e32 v55, v0
	v_mov_b32_e32 v8, v0
	v_mov_b32_e32 v9, v0
	v_mov_b32_e32 v10, v0
	v_mov_b32_e32 v11, v0
	v_mov_b32_e32 v12, v0
	v_mov_b32_e32 v13, v0
	v_mov_b32_e32 v14, v0
	v_mov_b32_e32 v15, v0
	v_mov_b32_e32 v24, v0
	v_mov_b32_e32 v25, v0
	v_mov_b32_e32 v26, v0
	v_mov_b32_e32 v27, v0
	v_mov_b32_e32 v28, v0
	v_mov_b32_e32 v29, v0
	v_mov_b32_e32 v30, v0
	v_mov_b32_e32 v31, v0
	v_mov_b32_e32 v40, v0
	v_mov_b32_e32 v41, v0
	v_mov_b32_e32 v42, v0
	v_mov_b32_e32 v43, v0
	v_mov_b32_e32 v44, v0
	v_mov_b32_e32 v45, v0
	v_mov_b32_e32 v46, v0
	v_mov_b32_e32 v47, v0
	v_mov_b32_e32 v56, v0
	v_mov_b32_e32 v57, v0
	v_mov_b32_e32 v58, v0
	v_mov_b32_e32 v59, v0
	v_mov_b32_e32 v60, v0
	v_mov_b32_e32 v61, v0
	v_mov_b32_e32 v62, v0
	v_mov_b32_e32 v63, v0
	v_mov_b32_e32 v64, v0
	v_mov_b32_e32 v65, v0
	v_mov_b32_e32 v66, v0
	v_mov_b32_e32 v67, v0
	v_mov_b32_e32 v68, v0
	v_mov_b32_e32 v69, v0
	v_mov_b32_e32 v70, v0
	v_mov_b32_e32 v71, v0
	v_mov_b32_e32 v80, v0
	v_mov_b32_e32 v81, v0
	v_mov_b32_e32 v82, v0
	v_mov_b32_e32 v83, v0
	v_mov_b32_e32 v84, v0
	v_mov_b32_e32 v85, v0
	v_mov_b32_e32 v86, v0
	v_mov_b32_e32 v87, v0
	v_mov_b32_e32 v96, v0
	v_mov_b32_e32 v97, v0
	v_mov_b32_e32 v98, v0
	v_mov_b32_e32 v99, v0
	v_mov_b32_e32 v100, v0
	v_mov_b32_e32 v101, v0
	v_mov_b32_e32 v102, v0
	v_mov_b32_e32 v103, v0
	v_mov_b32_e32 v112, v0
	v_mov_b32_e32 v113, v0
	v_mov_b32_e32 v114, v0
	v_mov_b32_e32 v115, v0
	v_mov_b32_e32 v116, v0
	v_mov_b32_e32 v117, v0
	v_mov_b32_e32 v118, v0
	v_mov_b32_e32 v119, v0
	v_mov_b32_e32 v72, v0
	v_mov_b32_e32 v73, v0
	v_mov_b32_e32 v74, v0
	v_mov_b32_e32 v75, v0
	v_mov_b32_e32 v76, v0
	v_mov_b32_e32 v77, v0
	v_mov_b32_e32 v78, v0
	v_mov_b32_e32 v79, v0
	v_mov_b32_e32 v88, v0
	v_mov_b32_e32 v89, v0
	v_mov_b32_e32 v90, v0
	v_mov_b32_e32 v91, v0
	v_mov_b32_e32 v92, v0
	v_mov_b32_e32 v93, v0
	v_mov_b32_e32 v94, v0
	v_mov_b32_e32 v95, v0
	v_mov_b32_e32 v104, v0
	v_mov_b32_e32 v105, v0
	v_mov_b32_e32 v106, v0
	v_mov_b32_e32 v107, v0
	v_mov_b32_e32 v108, v0
	v_mov_b32_e32 v109, v0
	v_mov_b32_e32 v110, v0
	v_mov_b32_e32 v111, v0
	v_mov_b32_e32 v120, v0
	v_mov_b32_e32 v121, v0
	v_mov_b32_e32 v122, v0
	v_mov_b32_e32 v123, v0
	v_mov_b32_e32 v124, v0
	v_mov_b32_e32 v125, v0
	v_mov_b32_e32 v126, v0
	v_mov_b32_e32 v127, v0
	s_branch .LBB0_1046

.LBB0_1046:
	ds_read_b128 v[128:131], v207
	ds_read_b128 v[132:135], v207 offset:1024
	ds_read_b128 v[136:139], v207 offset:2048
	ds_read_b128 v[140:143], v207 offset:3072
	ds_read_b128 v[144:147], v209
	ds_read_b128 v[148:151], v209 offset:1024
	ds_read_b128 v[152:155], v209 offset:2048
	ds_read_b128 v[156:159], v209 offset:3072
	s_add_u32 s34, s30, 0xfffc0080
	s_addc_u32 s35, s31, -1
	s_cmp_eq_u32 s55, 12
	s_cselect_b32 s37, s21, s35
	s_cselect_b32 s36, s27, s34
	s_cselect_b32 s35, s19, s54
	s_cselect_b32 s34, s52, s53
	v_lshl_add_u64 v[216:217], s[30:31], 0, v[184:185]
	s_add_i32 m0, s29, 0xc000
	ds_read_b128 v[160:163], v210
	ds_read_b128 v[164:167], v210 offset:1024
	ds_read_b128 v[168:171], v210 offset:2048
	ds_read_b128 v[172:175], v210 offset:3072
	ds_read_b128 v[192:195], v210 offset:4096
	ds_read_b128 v[196:199], v210 offset:5120
	ds_read_b128 v[200:203], v210 offset:6144
	ds_read_b128 v[212:215], v210 offset:7168
	global_load_lds_dwordx4 v[216:217], off
	v_lshl_add_u64 v[216:217], s[30:31], 0, v[186:187]
	s_add_i32 m0, s29, 0xe000
	s_nop 0
	global_load_lds_dwordx4 v[216:217], off
	s_waitcnt vmcnt(8)
	s_waitcnt lgkmcnt(0)
	s_barrier
	s_setprio 1
	s_waitcnt lgkmcnt(0)
	v_mfma_f32_16x16x32_bf16 v[124:127], v[128:131], v[160:163], v[124:127]
	v_mfma_f32_16x16x32_bf16 v[120:123], v[136:139], v[160:163], v[120:123]
	v_mfma_f32_16x16x32_bf16 v[108:111], v[128:131], v[168:171], v[108:111]
	v_mfma_f32_16x16x32_bf16 v[104:107], v[136:139], v[168:171], v[104:107]
	v_mfma_f32_16x16x32_bf16 v[92:95], v[128:131], v[192:195], v[92:95]
	v_mfma_f32_16x16x32_bf16 v[88:91], v[136:139], v[192:195], v[88:91]
	v_mfma_f32_16x16x32_bf16 v[76:79], v[128:131], v[200:203], v[76:79]
	v_mfma_f32_16x16x32_bf16 v[72:75], v[136:139], v[200:203], v[72:75]
	v_mfma_f32_16x16x32_bf16 v[124:127], v[132:135], v[164:167], v[124:127]
	v_mfma_f32_16x16x32_bf16 v[120:123], v[140:143], v[164:167], v[120:123]
	v_mfma_f32_16x16x32_bf16 v[108:111], v[132:135], v[172:175], v[108:111]
	v_mfma_f32_16x16x32_bf16 v[104:107], v[140:143], v[172:175], v[104:107]
	v_mfma_f32_16x16x32_bf16 v[92:95], v[132:135], v[196:199], v[92:95]
	v_mfma_f32_16x16x32_bf16 v[88:91], v[140:143], v[196:199], v[88:91]
	v_mfma_f32_16x16x32_bf16 v[76:79], v[132:135], v[212:215], v[76:79]
	v_mfma_f32_16x16x32_bf16 v[72:75], v[140:143], v[212:215], v[72:75]
	s_setprio 0
	s_setprio 1
	v_mfma_f32_16x16x32_bf16 v[116:119], v[144:147], v[160:163], v[116:119]
	v_mfma_f32_16x16x32_bf16 v[112:115], v[152:155], v[160:163], v[112:115]
	v_mfma_f32_16x16x32_bf16 v[100:103], v[144:147], v[168:171], v[100:103]
	v_mfma_f32_16x16x32_bf16 v[96:99], v[152:155], v[168:171], v[96:99]
	v_mfma_f32_16x16x32_bf16 v[84:87], v[144:147], v[192:195], v[84:87]
	v_mfma_f32_16x16x32_bf16 v[80:83], v[152:155], v[192:195], v[80:83]
	v_mfma_f32_16x16x32_bf16 v[68:71], v[144:147], v[200:203], v[68:71]
	v_mfma_f32_16x16x32_bf16 v[64:67], v[152:155], v[200:203], v[64:67]
	v_mfma_f32_16x16x32_bf16 v[116:119], v[148:151], v[164:167], v[116:119]
	v_mfma_f32_16x16x32_bf16 v[112:115], v[156:159], v[164:167], v[112:115]
	v_mfma_f32_16x16x32_bf16 v[100:103], v[148:151], v[172:175], v[100:103]
	v_mfma_f32_16x16x32_bf16 v[96:99], v[156:159], v[172:175], v[96:99]
	v_mfma_f32_16x16x32_bf16 v[84:87], v[148:151], v[196:199], v[84:87]
	v_mfma_f32_16x16x32_bf16 v[80:83], v[156:159], v[196:199], v[80:83]
	v_mfma_f32_16x16x32_bf16 v[68:71], v[148:151], v[212:215], v[68:71]
	v_mfma_f32_16x16x32_bf16 v[64:67], v[156:159], v[212:215], v[64:67]
	s_setprio 0
	s_barrier
	s_add_i32 s56, s50, s40
	v_lshl_add_u64 v[216:217], s[34:35], 0, v[178:179]
	s_mov_b32 m0, s56
	ds_read_b128 v[160:163], v210 offset:16384
	ds_read_b128 v[164:167], v210 offset:17408
	ds_read_b128 v[168:171], v210 offset:18432
	ds_read_b128 v[172:175], v210 offset:19456
	ds_read_b128 v[192:195], v210 offset:20480
	ds_read_b128 v[196:199], v210 offset:21504
	ds_read_b128 v[200:203], v210 offset:22528
	ds_read_b128 v[212:215], v210 offset:23552
	global_load_lds_dwordx4 v[216:217], off
	s_add_i32 m0, s56, 0x2000
	s_add_u32 s56, s34, 0x40000
	v_lshl_add_u64 v[218:219], s[34:35], 0, v[182:183]
	s_addc_u32 s57, s35, 0
	s_add_i32 s58, s51, s40
	global_load_lds_dwordx4 v[218:219], off
	v_lshl_add_u64 v[220:221], s[56:57], 0, v[178:179]
	s_mov_b32 m0, s58
	v_lshl_add_u64 v[222:223], s[36:37], 0, v[180:181]
	global_load_lds_dwordx4 v[220:221], off
	v_lshl_add_u64 v[220:221], s[56:57], 0, v[182:183]
	s_add_i32 m0, s58, 0x2000
	s_nop 0
	global_load_lds_dwordx4 v[220:221], off
	v_lshl_add_u64 v[220:221], s[36:37], 0, v[176:177]
	s_mov_b32 m0, s29
	s_nop 0
	global_load_lds_dwordx4 v[220:221], off
	s_mov_b32 m0, s41
	s_nop 0
	global_load_lds_dwordx4 v[222:223], off
	s_waitcnt vmcnt(8)
	s_waitcnt lgkmcnt(0)
	s_barrier
	s_setprio 1
	s_waitcnt lgkmcnt(0)
	v_mfma_f32_16x16x32_bf16 v[60:63], v[128:131], v[160:163], v[60:63]
	v_mfma_f32_16x16x32_bf16 v[56:59], v[136:139], v[160:163], v[56:59]
	v_mfma_f32_16x16x32_bf16 v[44:47], v[128:131], v[168:171], v[44:47]
	v_mfma_f32_16x16x32_bf16 v[40:43], v[136:139], v[168:171], v[40:43]
	v_mfma_f32_16x16x32_bf16 v[28:31], v[128:131], v[192:195], v[28:31]
	v_mfma_f32_16x16x32_bf16 v[24:27], v[136:139], v[192:195], v[24:27]
	v_mfma_f32_16x16x32_bf16 v[12:15], v[128:131], v[200:203], v[12:15]
	v_mfma_f32_16x16x32_bf16 v[8:11], v[136:139], v[200:203], v[8:11]
	v_mfma_f32_16x16x32_bf16 v[60:63], v[132:135], v[164:167], v[60:63]
	v_mfma_f32_16x16x32_bf16 v[56:59], v[140:143], v[164:167], v[56:59]
	v_mfma_f32_16x16x32_bf16 v[44:47], v[132:135], v[172:175], v[44:47]
	v_mfma_f32_16x16x32_bf16 v[40:43], v[140:143], v[172:175], v[40:43]
	v_mfma_f32_16x16x32_bf16 v[28:31], v[132:135], v[196:199], v[28:31]
	v_mfma_f32_16x16x32_bf16 v[24:27], v[140:143], v[196:199], v[24:27]
	v_mfma_f32_16x16x32_bf16 v[12:15], v[132:135], v[212:215], v[12:15]
	v_mfma_f32_16x16x32_bf16 v[8:11], v[140:143], v[212:215], v[8:11]
	s_setprio 0
	s_setprio 1
	v_mfma_f32_16x16x32_bf16 v[52:55], v[144:147], v[160:163], v[52:55]
	v_mfma_f32_16x16x32_bf16 v[48:51], v[152:155], v[160:163], v[48:51]
	v_mfma_f32_16x16x32_bf16 v[36:39], v[144:147], v[168:171], v[36:39]
	v_mfma_f32_16x16x32_bf16 v[32:35], v[152:155], v[168:171], v[32:35]
	v_mfma_f32_16x16x32_bf16 v[20:23], v[144:147], v[192:195], v[20:23]
	v_mfma_f32_16x16x32_bf16 v[16:19], v[152:155], v[192:195], v[16:19]
	v_mfma_f32_16x16x32_bf16 v[4:7], v[144:147], v[200:203], v[4:7]
	v_mfma_f32_16x16x32_bf16 v[0:3], v[152:155], v[200:203], v[0:3]
	v_mfma_f32_16x16x32_bf16 v[52:55], v[148:151], v[164:167], v[52:55]
	v_mfma_f32_16x16x32_bf16 v[48:51], v[156:159], v[164:167], v[48:51]
	v_mfma_f32_16x16x32_bf16 v[36:39], v[148:151], v[172:175], v[36:39]
	v_mfma_f32_16x16x32_bf16 v[32:35], v[156:159], v[172:175], v[32:35]
	v_mfma_f32_16x16x32_bf16 v[20:23], v[148:151], v[196:199], v[20:23]
	v_mfma_f32_16x16x32_bf16 v[16:19], v[156:159], v[196:199], v[16:19]
	v_mfma_f32_16x16x32_bf16 v[4:7], v[148:151], v[212:215], v[4:7]
	v_mfma_f32_16x16x32_bf16 v[0:3], v[156:159], v[212:215], v[0:3]
	s_setprio 0
	s_barrier
	s_add_i32 s56, 0, 0x18000
	s_add_i32 s57, 0, 0x1c000
	v_add_u32_e32 v140, s56, v205
	v_add_u32_e32 v156, s57, v205
	ds_read_b128 v[128:131], v140
	ds_read_b128 v[132:135], v140 offset:1024
	ds_read_b128 v[136:139], v140 offset:2048
	ds_read_b128 v[140:143], v140 offset:3072
	ds_read_b128 v[144:147], v156
	ds_read_b128 v[148:151], v156 offset:1024
	ds_read_b128 v[152:155], v156 offset:2048
	ds_read_b128 v[156:159], v156 offset:3072
	s_add_u32 s36, s36, 0x40000
	s_addc_u32 s37, s37, 0
	s_mov_b32 m0, s42
	v_lshl_add_u64 v[224:225], s[36:37], 0, v[176:177]
	ds_read_b128 v[160:163], v210 offset:32768
	ds_read_b128 v[164:167], v210 offset:33792
	ds_read_b128 v[168:171], v210 offset:34816
	ds_read_b128 v[172:175], v210 offset:35840
	ds_read_b128 v[192:195], v210 offset:36864
	ds_read_b128 v[196:199], v210 offset:37888
	ds_read_b128 v[200:203], v210 offset:38912
	ds_read_b128 v[212:215], v210 offset:39936
	global_load_lds_dwordx4 v[224:225], off
	v_lshl_add_u64 v[224:225], s[36:37], 0, v[180:181]
	s_mov_b32 m0, s43
	s_nop 0
	global_load_lds_dwordx4 v[224:225], off
	s_waitcnt vmcnt(8)
	s_waitcnt lgkmcnt(0)
	s_barrier
	s_setprio 1
	s_waitcnt lgkmcnt(0)
	v_mfma_f32_16x16x32_bf16 v[124:127], v[128:131], v[160:163], v[124:127]
	v_mfma_f32_16x16x32_bf16 v[120:123], v[136:139], v[160:163], v[120:123]
	v_mfma_f32_16x16x32_bf16 v[108:111], v[128:131], v[168:171], v[108:111]
	v_mfma_f32_16x16x32_bf16 v[104:107], v[136:139], v[168:171], v[104:107]
	v_mfma_f32_16x16x32_bf16 v[92:95], v[128:131], v[192:195], v[92:95]
	v_mfma_f32_16x16x32_bf16 v[88:91], v[136:139], v[192:195], v[88:91]
	v_mfma_f32_16x16x32_bf16 v[76:79], v[128:131], v[200:203], v[76:79]
	v_mfma_f32_16x16x32_bf16 v[72:75], v[136:139], v[200:203], v[72:75]
	v_mfma_f32_16x16x32_bf16 v[124:127], v[132:135], v[164:167], v[124:127]
	v_mfma_f32_16x16x32_bf16 v[120:123], v[140:143], v[164:167], v[120:123]
	v_mfma_f32_16x16x32_bf16 v[108:111], v[132:135], v[172:175], v[108:111]
	v_mfma_f32_16x16x32_bf16 v[104:107], v[140:143], v[172:175], v[104:107]
	v_mfma_f32_16x16x32_bf16 v[92:95], v[132:135], v[196:199], v[92:95]
	v_mfma_f32_16x16x32_bf16 v[88:91], v[140:143], v[196:199], v[88:91]
	v_mfma_f32_16x16x32_bf16 v[76:79], v[132:135], v[212:215], v[76:79]
	v_mfma_f32_16x16x32_bf16 v[72:75], v[140:143], v[212:215], v[72:75]
	s_setprio 0
	s_setprio 1
	v_mfma_f32_16x16x32_bf16 v[116:119], v[144:147], v[160:163], v[116:119]
	v_mfma_f32_16x16x32_bf16 v[112:115], v[152:155], v[160:163], v[112:115]
	v_mfma_f32_16x16x32_bf16 v[100:103], v[144:147], v[168:171], v[100:103]
	v_mfma_f32_16x16x32_bf16 v[96:99], v[152:155], v[168:171], v[96:99]
	v_mfma_f32_16x16x32_bf16 v[84:87], v[144:147], v[192:195], v[84:87]
	v_mfma_f32_16x16x32_bf16 v[80:83], v[152:155], v[192:195], v[80:83]
	v_mfma_f32_16x16x32_bf16 v[68:71], v[144:147], v[200:203], v[68:71]
	v_mfma_f32_16x16x32_bf16 v[64:67], v[152:155], v[200:203], v[64:67]
	v_mfma_f32_16x16x32_bf16 v[116:119], v[148:151], v[164:167], v[116:119]
	v_mfma_f32_16x16x32_bf16 v[112:115], v[156:159], v[164:167], v[112:115]
	v_mfma_f32_16x16x32_bf16 v[100:103], v[148:151], v[172:175], v[100:103]
	v_mfma_f32_16x16x32_bf16 v[96:99], v[156:159], v[172:175], v[96:99]
	v_mfma_f32_16x16x32_bf16 v[84:87], v[148:151], v[196:199], v[84:87]
	v_mfma_f32_16x16x32_bf16 v[80:83], v[156:159], v[196:199], v[80:83]
	v_mfma_f32_16x16x32_bf16 v[68:71], v[148:151], v[212:215], v[68:71]
	v_mfma_f32_16x16x32_bf16 v[64:67], v[156:159], v[212:215], v[64:67]
	s_setprio 0
	s_barrier
	s_add_i32 s36, s56, s40
	v_lshl_add_u64 v[216:217], v[216:217], 0, s[14:15]
	s_mov_b32 m0, s36
	ds_read_b128 v[160:163], v210 offset:49152
	ds_read_b128 v[164:167], v210 offset:50176
	ds_read_b128 v[168:171], v210 offset:51200
	ds_read_b128 v[172:175], v210 offset:52224
	ds_read_b128 v[192:195], v210 offset:53248
	ds_read_b128 v[196:199], v210 offset:54272
	ds_read_b128 v[200:203], v210 offset:55296
	ds_read_b128 v[212:215], v210 offset:56320
	global_load_lds_dwordx4 v[216:217], off
	s_add_i32 m0, s36, 0x2000
	s_add_u32 s34, s34, 0x40080
	v_lshl_add_u64 v[216:217], v[218:219], 0, s[14:15]
	s_addc_u32 s35, s35, 0
	s_add_i32 s36, s57, s40
	global_load_lds_dwordx4 v[216:217], off
	v_lshl_add_u64 v[216:217], s[34:35], 0, v[178:179]
	s_mov_b32 m0, s36
	s_nop 0
	global_load_lds_dwordx4 v[216:217], off
	v_lshl_add_u64 v[216:217], s[34:35], 0, v[182:183]
	s_add_i32 m0, s36, 0x2000
	s_nop 0
	global_load_lds_dwordx4 v[216:217], off
	v_lshl_add_u64 v[216:217], v[220:221], 0, s[14:15]
	s_mov_b32 m0, s45
	s_nop 0
	global_load_lds_dwordx4 v[216:217], off
	v_lshl_add_u64 v[216:217], v[222:223], 0, s[14:15]
	s_mov_b32 m0, s46
	s_nop 0
	global_load_lds_dwordx4 v[216:217], off
	s_waitcnt vmcnt(8)
	s_waitcnt lgkmcnt(0)
	s_barrier
	s_setprio 1
	s_waitcnt lgkmcnt(0)
	v_mfma_f32_16x16x32_bf16 v[60:63], v[128:131], v[160:163], v[60:63]
	v_mfma_f32_16x16x32_bf16 v[56:59], v[136:139], v[160:163], v[56:59]
	v_mfma_f32_16x16x32_bf16 v[44:47], v[128:131], v[168:171], v[44:47]
	v_mfma_f32_16x16x32_bf16 v[40:43], v[136:139], v[168:171], v[40:43]
	v_mfma_f32_16x16x32_bf16 v[28:31], v[128:131], v[192:195], v[28:31]
	v_mfma_f32_16x16x32_bf16 v[24:27], v[136:139], v[192:195], v[24:27]
	v_mfma_f32_16x16x32_bf16 v[12:15], v[128:131], v[200:203], v[12:15]
	v_mfma_f32_16x16x32_bf16 v[8:11], v[136:139], v[200:203], v[8:11]
	v_mfma_f32_16x16x32_bf16 v[60:63], v[132:135], v[164:167], v[60:63]
	v_mfma_f32_16x16x32_bf16 v[56:59], v[140:143], v[164:167], v[56:59]
	v_mfma_f32_16x16x32_bf16 v[44:47], v[132:135], v[172:175], v[44:47]
	v_mfma_f32_16x16x32_bf16 v[40:43], v[140:143], v[172:175], v[40:43]
	v_mfma_f32_16x16x32_bf16 v[28:31], v[132:135], v[196:199], v[28:31]
	v_mfma_f32_16x16x32_bf16 v[24:27], v[140:143], v[196:199], v[24:27]
	v_mfma_f32_16x16x32_bf16 v[12:15], v[132:135], v[212:215], v[12:15]
	v_mfma_f32_16x16x32_bf16 v[8:11], v[140:143], v[212:215], v[8:11]
	s_setprio 0
	s_setprio 1
	v_mfma_f32_16x16x32_bf16 v[52:55], v[144:147], v[160:163], v[52:55]
	v_mfma_f32_16x16x32_bf16 v[48:51], v[152:155], v[160:163], v[48:51]
	v_mfma_f32_16x16x32_bf16 v[36:39], v[144:147], v[168:171], v[36:39]
	v_mfma_f32_16x16x32_bf16 v[32:35], v[152:155], v[168:171], v[32:35]
	v_mfma_f32_16x16x32_bf16 v[20:23], v[144:147], v[192:195], v[20:23]
	v_mfma_f32_16x16x32_bf16 v[16:19], v[152:155], v[192:195], v[16:19]
	v_mfma_f32_16x16x32_bf16 v[4:7], v[144:147], v[200:203], v[4:7]
	v_mfma_f32_16x16x32_bf16 v[0:3], v[152:155], v[200:203], v[0:3]
	v_mfma_f32_16x16x32_bf16 v[52:55], v[148:151], v[164:167], v[52:55]
	v_mfma_f32_16x16x32_bf16 v[48:51], v[156:159], v[164:167], v[48:51]
	v_mfma_f32_16x16x32_bf16 v[36:39], v[148:151], v[172:175], v[36:39]
	v_mfma_f32_16x16x32_bf16 v[32:35], v[156:159], v[172:175], v[32:35]
	v_mfma_f32_16x16x32_bf16 v[20:23], v[148:151], v[196:199], v[20:23]
	v_mfma_f32_16x16x32_bf16 v[16:19], v[156:159], v[196:199], v[16:19]
	v_mfma_f32_16x16x32_bf16 v[4:7], v[148:151], v[212:215], v[4:7]
	v_mfma_f32_16x16x32_bf16 v[0:3], v[156:159], v[212:215], v[0:3]
	s_setprio 0
	s_add_i32 s55, s55, 2
	s_add_u32 s30, s30, 0x100
	s_addc_u32 s31, s31, 0
	s_add_u32 s53, s53, 0x100
	s_addc_u32 s54, s54, 0
	s_cmp_gt_u32 s55, 13
	s_cbranch_scc0 .Lrot2_head
	s_barrier
	s_and_b64 vcc, exec, s[16:17]
	s_cbranch_vccz .LBB0_1049
	s_barrier

.LBB0_1128:
	s_ashr_i32 s21, s20, 31
	s_lshl_b64 s[22:23], s[20:21], 19
	s_add_u32 s22, s3, s22
	s_addc_u32 s23, s33, s23
	s_and_b64 s[24:25], s[0:1], exec
	s_cselect_b32 s21, s23, s27
	s_cselect_b32 s52, s22, s26
	s_ashr_i32 s19, s18, 31
	s_lshl_b64 s[24:25], s[18:19], 19
	s_add_u32 s24, s34, s24
	s_addc_u32 s25, s35, s25
	s_and_b64 s[30:31], s[0:1], exec
	s_cselect_b32 s19, s25, s29
	s_cselect_b32 s53, s24, s28
	s_add_u32 s26, s26, 0x40080
	s_addc_u32 s27, s27, 0
	s_add_u32 s54, s28, 0x100
	v_mov_b32_e32 v0, 0
	s_addc_u32 s55, s29, 0
	s_mov_b32 s56, -2
	v_mov_b32_e32 v1, v0
	v_mov_b32_e32 v2, v0
	v_mov_b32_e32 v3, v0
	v_mov_b32_e32 v4, v0
	v_mov_b32_e32 v5, v0
	v_mov_b32_e32 v6, v0
	v_mov_b32_e32 v7, v0
	v_mov_b32_e32 v16, v0
	v_mov_b32_e32 v17, v0
	v_mov_b32_e32 v18, v0
	v_mov_b32_e32 v19, v0
	v_mov_b32_e32 v20, v0
	v_mov_b32_e32 v21, v0
	v_mov_b32_e32 v22, v0
	v_mov_b32_e32 v23, v0
	v_mov_b32_e32 v32, v0
	v_mov_b32_e32 v33, v0
	v_mov_b32_e32 v34, v0
	v_mov_b32_e32 v35, v0
	v_mov_b32_e32 v36, v0
	v_mov_b32_e32 v37, v0
	v_mov_b32_e32 v38, v0
	v_mov_b32_e32 v39, v0
	v_mov_b32_e32 v48, v0
	v_mov_b32_e32 v49, v0
	v_mov_b32_e32 v50, v0
	v_mov_b32_e32 v51, v0
	v_mov_b32_e32 v52, v0
	v_mov_b32_e32 v53, v0
	v_mov_b32_e32 v54, v0
	v_mov_b32_e32 v55, v0
	v_mov_b32_e32 v8, v0
	v_mov_b32_e32 v9, v0
	v_mov_b32_e32 v10, v0
	v_mov_b32_e32 v11, v0
	v_mov_b32_e32 v12, v0
	v_mov_b32_e32 v13, v0
	v_mov_b32_e32 v14, v0
	v_mov_b32_e32 v15, v0
	v_mov_b32_e32 v24, v0
	v_mov_b32_e32 v25, v0
	v_mov_b32_e32 v26, v0
	v_mov_b32_e32 v27, v0
	v_mov_b32_e32 v28, v0
	v_mov_b32_e32 v29, v0
	v_mov_b32_e32 v30, v0
	v_mov_b32_e32 v31, v0
	v_mov_b32_e32 v40, v0
	v_mov_b32_e32 v41, v0
	v_mov_b32_e32 v42, v0
	v_mov_b32_e32 v43, v0
	v_mov_b32_e32 v44, v0
	v_mov_b32_e32 v45, v0
	v_mov_b32_e32 v46, v0
	v_mov_b32_e32 v47, v0
	v_mov_b32_e32 v56, v0
	v_mov_b32_e32 v57, v0
	v_mov_b32_e32 v58, v0
	v_mov_b32_e32 v59, v0
	v_mov_b32_e32 v60, v0
	v_mov_b32_e32 v61, v0
	v_mov_b32_e32 v62, v0
	v_mov_b32_e32 v63, v0
	v_mov_b32_e32 v64, v0
	v_mov_b32_e32 v65, v0
	v_mov_b32_e32 v66, v0
	v_mov_b32_e32 v67, v0
	v_mov_b32_e32 v68, v0
	v_mov_b32_e32 v69, v0
	v_mov_b32_e32 v70, v0
	v_mov_b32_e32 v71, v0
	v_mov_b32_e32 v80, v0
	v_mov_b32_e32 v81, v0
	v_mov_b32_e32 v82, v0
	v_mov_b32_e32 v83, v0
	v_mov_b32_e32 v84, v0
	v_mov_b32_e32 v85, v0
	v_mov_b32_e32 v86, v0
	v_mov_b32_e32 v87, v0
	v_mov_b32_e32 v96, v0
	v_mov_b32_e32 v97, v0
	v_mov_b32_e32 v98, v0
	v_mov_b32_e32 v99, v0
	v_mov_b32_e32 v100, v0
	v_mov_b32_e32 v101, v0
	v_mov_b32_e32 v102, v0
	v_mov_b32_e32 v103, v0
	v_mov_b32_e32 v112, v0
	v_mov_b32_e32 v113, v0
	v_mov_b32_e32 v114, v0
	v_mov_b32_e32 v115, v0
	v_mov_b32_e32 v116, v0
	v_mov_b32_e32 v117, v0
	v_mov_b32_e32 v118, v0
	v_mov_b32_e32 v119, v0
	v_mov_b32_e32 v72, v0
	v_mov_b32_e32 v73, v0
	v_mov_b32_e32 v74, v0
	v_mov_b32_e32 v75, v0
	v_mov_b32_e32 v76, v0
	v_mov_b32_e32 v77, v0
	v_mov_b32_e32 v78, v0
	v_mov_b32_e32 v79, v0
	v_mov_b32_e32 v88, v0
	v_mov_b32_e32 v89, v0
	v_mov_b32_e32 v90, v0
	v_mov_b32_e32 v91, v0
	v_mov_b32_e32 v92, v0
	v_mov_b32_e32 v93, v0
	v_mov_b32_e32 v94, v0
	v_mov_b32_e32 v95, v0
	v_mov_b32_e32 v104, v0
	v_mov_b32_e32 v105, v0
	v_mov_b32_e32 v106, v0
	v_mov_b32_e32 v107, v0
	v_mov_b32_e32 v108, v0
	v_mov_b32_e32 v109, v0
	v_mov_b32_e32 v110, v0
	v_mov_b32_e32 v111, v0
	v_mov_b32_e32 v120, v0
	v_mov_b32_e32 v121, v0
	v_mov_b32_e32 v122, v0
	v_mov_b32_e32 v123, v0
	v_mov_b32_e32 v124, v0
	v_mov_b32_e32 v125, v0
	v_mov_b32_e32 v126, v0
	v_mov_b32_e32 v127, v0
	s_branch .LBB0_1129

.LBB0_1129:
	ds_read_b128 v[144:147], v157
	ds_read_b128 v[148:151], v157 offset:1024
	ds_read_b128 v[162:165], v157 offset:2048
	ds_read_b128 v[166:169], v157 offset:3072
	ds_read_b128 v[170:173], v158
	ds_read_b128 v[174:177], v158 offset:1024
	ds_read_b128 v[178:181], v158 offset:2048
	ds_read_b128 v[182:185], v158 offset:3072
	s_add_u32 s28, s26, 0xfffc0080
	s_addc_u32 s29, s27, -1
	s_cmp_eq_u32 s56, 12
	s_cselect_b32 s31, s21, s29
	s_cselect_b32 s30, s52, s28
	s_cselect_b32 s29, s19, s55
	s_cselect_b32 s28, s53, s54
	v_lshl_add_u64 v[152:153], s[26:27], 0, v[136:137]
	s_add_i32 m0, s39, 0xc000
	ds_read_b128 v[186:189], v159
	ds_read_b128 v[190:193], v159 offset:1024
	ds_read_b128 v[194:197], v159 offset:2048
	ds_read_b128 v[198:201], v159 offset:3072
	ds_read_b128 v[202:205], v159 offset:4096
	ds_read_b128 v[210:213], v159 offset:5120
	ds_read_b128 v[214:217], v159 offset:6144
	ds_read_b128 v[218:221], v159 offset:7168
	global_load_lds_dwordx4 v[152:153], off
	v_lshl_add_u64 v[152:153], s[26:27], 0, v[138:139]
	s_add_i32 m0, s39, 0xe000
	s_nop 0
	global_load_lds_dwordx4 v[152:153], off
	s_waitcnt vmcnt(8)
	s_waitcnt lgkmcnt(0)
	s_barrier
	s_setprio 1
	s_waitcnt lgkmcnt(0)
	v_mfma_f32_16x16x32_bf16 v[124:127], v[144:147], v[186:189], v[124:127]
	v_mfma_f32_16x16x32_bf16 v[120:123], v[162:165], v[186:189], v[120:123]
	v_mfma_f32_16x16x32_bf16 v[108:111], v[144:147], v[194:197], v[108:111]
	v_mfma_f32_16x16x32_bf16 v[104:107], v[162:165], v[194:197], v[104:107]
	v_mfma_f32_16x16x32_bf16 v[92:95], v[144:147], v[202:205], v[92:95]
	v_mfma_f32_16x16x32_bf16 v[88:91], v[162:165], v[202:205], v[88:91]
	v_mfma_f32_16x16x32_bf16 v[76:79], v[144:147], v[214:217], v[76:79]
	v_mfma_f32_16x16x32_bf16 v[72:75], v[162:165], v[214:217], v[72:75]
	v_mfma_f32_16x16x32_bf16 v[124:127], v[148:151], v[190:193], v[124:127]
	v_mfma_f32_16x16x32_bf16 v[120:123], v[166:169], v[190:193], v[120:123]
	v_mfma_f32_16x16x32_bf16 v[108:111], v[148:151], v[198:201], v[108:111]
	v_mfma_f32_16x16x32_bf16 v[104:107], v[166:169], v[198:201], v[104:107]
	v_mfma_f32_16x16x32_bf16 v[92:95], v[148:151], v[210:213], v[92:95]
	v_mfma_f32_16x16x32_bf16 v[88:91], v[166:169], v[210:213], v[88:91]
	v_mfma_f32_16x16x32_bf16 v[76:79], v[148:151], v[218:221], v[76:79]
	v_mfma_f32_16x16x32_bf16 v[72:75], v[166:169], v[218:221], v[72:75]
	s_setprio 0
	s_setprio 1
	v_mfma_f32_16x16x32_bf16 v[116:119], v[170:173], v[186:189], v[116:119]
	v_mfma_f32_16x16x32_bf16 v[112:115], v[178:181], v[186:189], v[112:115]
	v_mfma_f32_16x16x32_bf16 v[100:103], v[170:173], v[194:197], v[100:103]
	v_mfma_f32_16x16x32_bf16 v[96:99], v[178:181], v[194:197], v[96:99]
	v_mfma_f32_16x16x32_bf16 v[84:87], v[170:173], v[202:205], v[84:87]
	v_mfma_f32_16x16x32_bf16 v[80:83], v[178:181], v[202:205], v[80:83]
	v_mfma_f32_16x16x32_bf16 v[68:71], v[170:173], v[214:217], v[68:71]
	v_mfma_f32_16x16x32_bf16 v[64:67], v[178:181], v[214:217], v[64:67]
	v_mfma_f32_16x16x32_bf16 v[116:119], v[174:177], v[190:193], v[116:119]
	v_mfma_f32_16x16x32_bf16 v[112:115], v[182:185], v[190:193], v[112:115]
	v_mfma_f32_16x16x32_bf16 v[100:103], v[174:177], v[198:201], v[100:103]
	v_mfma_f32_16x16x32_bf16 v[96:99], v[182:185], v[198:201], v[96:99]
	v_mfma_f32_16x16x32_bf16 v[84:87], v[174:177], v[210:213], v[84:87]
	v_mfma_f32_16x16x32_bf16 v[80:83], v[182:185], v[210:213], v[80:83]
	v_mfma_f32_16x16x32_bf16 v[68:71], v[174:177], v[218:221], v[68:71]
	v_mfma_f32_16x16x32_bf16 v[64:67], v[182:185], v[218:221], v[64:67]
	s_setprio 0
	s_barrier
	s_add_i32 s57, s48, s36
	v_lshl_add_u64 v[152:153], s[28:29], 0, v[132:133]
	s_mov_b32 m0, s57
	ds_read_b128 v[186:189], v159 offset:16384
	ds_read_b128 v[190:193], v159 offset:17408
	ds_read_b128 v[194:197], v159 offset:18432
	ds_read_b128 v[198:201], v159 offset:19456
	ds_read_b128 v[202:205], v159 offset:20480
	ds_read_b128 v[210:213], v159 offset:21504
	ds_read_b128 v[214:217], v159 offset:22528
	ds_read_b128 v[218:221], v159 offset:23552
	global_load_lds_dwordx4 v[152:153], off
	s_add_i32 m0, s57, 0x2000
	s_add_u32 s58, s28, 0x40000
	v_lshl_add_u64 v[206:207], s[28:29], 0, v[128:129]
	s_addc_u32 s59, s29, 0
	s_add_i32 s57, s49, s36
	global_load_lds_dwordx4 v[206:207], off
	v_lshl_add_u64 v[222:223], s[58:59], 0, v[132:133]
	s_mov_b32 m0, s57
	v_lshl_add_u64 v[224:225], s[30:31], 0, v[130:131]
	global_load_lds_dwordx4 v[222:223], off
	v_lshl_add_u64 v[222:223], s[58:59], 0, v[128:129]
	s_add_i32 m0, s57, 0x2000
	s_nop 0
	global_load_lds_dwordx4 v[222:223], off
	v_lshl_add_u64 v[222:223], s[30:31], 0, v[134:135]
	s_mov_b32 m0, s39
	s_nop 0
	global_load_lds_dwordx4 v[222:223], off
	s_mov_b32 m0, s40
	s_nop 0
	global_load_lds_dwordx4 v[224:225], off
	s_waitcnt vmcnt(8)
	s_waitcnt lgkmcnt(0)
	s_barrier
	s_setprio 1
	s_waitcnt lgkmcnt(0)
	v_mfma_f32_16x16x32_bf16 v[60:63], v[144:147], v[186:189], v[60:63]
	v_mfma_f32_16x16x32_bf16 v[56:59], v[162:165], v[186:189], v[56:59]
	v_mfma_f32_16x16x32_bf16 v[44:47], v[144:147], v[194:197], v[44:47]
	v_mfma_f32_16x16x32_bf16 v[40:43], v[162:165], v[194:197], v[40:43]
	v_mfma_f32_16x16x32_bf16 v[28:31], v[144:147], v[202:205], v[28:31]
	v_mfma_f32_16x16x32_bf16 v[24:27], v[162:165], v[202:205], v[24:27]
	v_mfma_f32_16x16x32_bf16 v[12:15], v[144:147], v[214:217], v[12:15]
	v_mfma_f32_16x16x32_bf16 v[8:11], v[162:165], v[214:217], v[8:11]
	v_mfma_f32_16x16x32_bf16 v[60:63], v[148:151], v[190:193], v[60:63]
	v_mfma_f32_16x16x32_bf16 v[56:59], v[166:169], v[190:193], v[56:59]
	v_mfma_f32_16x16x32_bf16 v[44:47], v[148:151], v[198:201], v[44:47]
	v_mfma_f32_16x16x32_bf16 v[40:43], v[166:169], v[198:201], v[40:43]
	v_mfma_f32_16x16x32_bf16 v[28:31], v[148:151], v[210:213], v[28:31]
	v_mfma_f32_16x16x32_bf16 v[24:27], v[166:169], v[210:213], v[24:27]
	v_mfma_f32_16x16x32_bf16 v[12:15], v[148:151], v[218:221], v[12:15]
	v_mfma_f32_16x16x32_bf16 v[8:11], v[166:169], v[218:221], v[8:11]
	s_setprio 0
	s_setprio 1
	v_mfma_f32_16x16x32_bf16 v[52:55], v[170:173], v[186:189], v[52:55]
	v_mfma_f32_16x16x32_bf16 v[48:51], v[178:181], v[186:189], v[48:51]
	v_mfma_f32_16x16x32_bf16 v[36:39], v[170:173], v[194:197], v[36:39]
	v_mfma_f32_16x16x32_bf16 v[32:35], v[178:181], v[194:197], v[32:35]
	v_mfma_f32_16x16x32_bf16 v[20:23], v[170:173], v[202:205], v[20:23]
	v_mfma_f32_16x16x32_bf16 v[16:19], v[178:181], v[202:205], v[16:19]
	v_mfma_f32_16x16x32_bf16 v[4:7], v[170:173], v[214:217], v[4:7]
	v_mfma_f32_16x16x32_bf16 v[0:3], v[178:181], v[214:217], v[0:3]
	v_mfma_f32_16x16x32_bf16 v[52:55], v[174:177], v[190:193], v[52:55]
	v_mfma_f32_16x16x32_bf16 v[48:51], v[182:185], v[190:193], v[48:51]
	v_mfma_f32_16x16x32_bf16 v[36:39], v[174:177], v[198:201], v[36:39]
	v_mfma_f32_16x16x32_bf16 v[32:35], v[182:185], v[198:201], v[32:35]
	v_mfma_f32_16x16x32_bf16 v[20:23], v[174:177], v[210:213], v[20:23]
	v_mfma_f32_16x16x32_bf16 v[16:19], v[182:185], v[210:213], v[16:19]
	v_mfma_f32_16x16x32_bf16 v[4:7], v[174:177], v[218:221], v[4:7]
	v_mfma_f32_16x16x32_bf16 v[0:3], v[182:185], v[218:221], v[0:3]
	s_setprio 0
	s_barrier
	s_add_i32 s57, 0, 0x18000
	v_add_u32_e32 v161, s57, v155
	s_add_i32 s58, 0, 0x1c000
	ds_read_b128 v[144:147], v161
	ds_read_b128 v[148:151], v161 offset:1024
	ds_read_b128 v[162:165], v161 offset:2048
	ds_read_b128 v[166:169], v161 offset:3072
	v_add_u32_e32 v161, s58, v155
	ds_read_b128 v[170:173], v161
	ds_read_b128 v[174:177], v161 offset:1024
	ds_read_b128 v[178:181], v161 offset:2048
	ds_read_b128 v[182:185], v161 offset:3072
	s_add_u32 s30, s30, 0x40000
	s_addc_u32 s31, s31, 0
	s_mov_b32 m0, s41
	v_lshl_add_u64 v[226:227], s[30:31], 0, v[134:135]
	ds_read_b128 v[186:189], v159 offset:32768
	ds_read_b128 v[190:193], v159 offset:33792
	ds_read_b128 v[194:197], v159 offset:34816
	ds_read_b128 v[198:201], v159 offset:35840
	ds_read_b128 v[202:205], v159 offset:36864
	ds_read_b128 v[210:213], v159 offset:37888
	ds_read_b128 v[214:217], v159 offset:38912
	ds_read_b128 v[218:221], v159 offset:39936
	global_load_lds_dwordx4 v[226:227], off
	v_lshl_add_u64 v[226:227], s[30:31], 0, v[130:131]
	s_mov_b32 m0, s42
	s_nop 0
	global_load_lds_dwordx4 v[226:227], off
	s_waitcnt vmcnt(8)
	s_waitcnt lgkmcnt(0)
	s_barrier
	s_setprio 1
	s_waitcnt lgkmcnt(0)
	v_mfma_f32_16x16x32_bf16 v[124:127], v[144:147], v[186:189], v[124:127]
	v_mfma_f32_16x16x32_bf16 v[120:123], v[162:165], v[186:189], v[120:123]
	v_mfma_f32_16x16x32_bf16 v[108:111], v[144:147], v[194:197], v[108:111]
	v_mfma_f32_16x16x32_bf16 v[104:107], v[162:165], v[194:197], v[104:107]
	v_mfma_f32_16x16x32_bf16 v[92:95], v[144:147], v[202:205], v[92:95]
	v_mfma_f32_16x16x32_bf16 v[88:91], v[162:165], v[202:205], v[88:91]
	v_mfma_f32_16x16x32_bf16 v[76:79], v[144:147], v[214:217], v[76:79]
	v_mfma_f32_16x16x32_bf16 v[72:75], v[162:165], v[214:217], v[72:75]
	v_mfma_f32_16x16x32_bf16 v[124:127], v[148:151], v[190:193], v[124:127]
	v_mfma_f32_16x16x32_bf16 v[120:123], v[166:169], v[190:193], v[120:123]
	v_mfma_f32_16x16x32_bf16 v[108:111], v[148:151], v[198:201], v[108:111]
	v_mfma_f32_16x16x32_bf16 v[104:107], v[166:169], v[198:201], v[104:107]
	v_mfma_f32_16x16x32_bf16 v[92:95], v[148:151], v[210:213], v[92:95]
	v_mfma_f32_16x16x32_bf16 v[88:91], v[166:169], v[210:213], v[88:91]
	v_mfma_f32_16x16x32_bf16 v[76:79], v[148:151], v[218:221], v[76:79]
	v_mfma_f32_16x16x32_bf16 v[72:75], v[166:169], v[218:221], v[72:75]
	s_setprio 0
	s_setprio 1
	v_mfma_f32_16x16x32_bf16 v[116:119], v[170:173], v[186:189], v[116:119]
	v_mfma_f32_16x16x32_bf16 v[112:115], v[178:181], v[186:189], v[112:115]
	v_mfma_f32_16x16x32_bf16 v[100:103], v[170:173], v[194:197], v[100:103]
	v_mfma_f32_16x16x32_bf16 v[96:99], v[178:181], v[194:197], v[96:99]
	v_mfma_f32_16x16x32_bf16 v[84:87], v[170:173], v[202:205], v[84:87]
	v_mfma_f32_16x16x32_bf16 v[80:83], v[178:181], v[202:205], v[80:83]
	v_mfma_f32_16x16x32_bf16 v[68:71], v[170:173], v[214:217], v[68:71]
	v_mfma_f32_16x16x32_bf16 v[64:67], v[178:181], v[214:217], v[64:67]
	v_mfma_f32_16x16x32_bf16 v[116:119], v[174:177], v[190:193], v[116:119]
	v_mfma_f32_16x16x32_bf16 v[112:115], v[182:185], v[190:193], v[112:115]
	v_mfma_f32_16x16x32_bf16 v[100:103], v[174:177], v[198:201], v[100:103]
	v_mfma_f32_16x16x32_bf16 v[96:99], v[182:185], v[198:201], v[96:99]
	v_mfma_f32_16x16x32_bf16 v[84:87], v[174:177], v[210:213], v[84:87]
	v_mfma_f32_16x16x32_bf16 v[80:83], v[182:185], v[210:213], v[80:83]
	v_mfma_f32_16x16x32_bf16 v[68:71], v[174:177], v[218:221], v[68:71]
	v_mfma_f32_16x16x32_bf16 v[64:67], v[182:185], v[218:221], v[64:67]
	s_setprio 0
	s_barrier
	s_add_i32 s30, s57, s36
	v_lshl_add_u64 v[152:153], v[152:153], 0, s[14:15]
	s_mov_b32 m0, s30
	ds_read_b128 v[186:189], v159 offset:49152
	ds_read_b128 v[190:193], v159 offset:50176
	ds_read_b128 v[194:197], v159 offset:51200
	ds_read_b128 v[198:201], v159 offset:52224
	ds_read_b128 v[202:205], v159 offset:53248
	ds_read_b128 v[210:213], v159 offset:54272
	ds_read_b128 v[214:217], v159 offset:55296
	ds_read_b128 v[218:221], v159 offset:56320
	global_load_lds_dwordx4 v[152:153], off
	s_add_i32 m0, s30, 0x2000
	s_add_u32 s28, s28, 0x40080
	v_lshl_add_u64 v[152:153], v[206:207], 0, s[14:15]
	s_addc_u32 s29, s29, 0
	s_add_i32 s30, s58, s36
	global_load_lds_dwordx4 v[152:153], off
	v_lshl_add_u64 v[152:153], s[28:29], 0, v[132:133]
	s_mov_b32 m0, s30
	s_nop 0
	global_load_lds_dwordx4 v[152:153], off
	v_lshl_add_u64 v[152:153], s[28:29], 0, v[128:129]
	s_add_i32 m0, s30, 0x2000
	s_nop 0
	global_load_lds_dwordx4 v[152:153], off
	v_lshl_add_u64 v[152:153], v[222:223], 0, s[14:15]
	s_mov_b32 m0, s44
	s_nop 0
	global_load_lds_dwordx4 v[152:153], off
	v_lshl_add_u64 v[152:153], v[224:225], 0, s[14:15]
	s_mov_b32 m0, s45
	s_nop 0
	global_load_lds_dwordx4 v[152:153], off
	s_waitcnt vmcnt(8)
	s_waitcnt lgkmcnt(0)
	s_barrier
	s_setprio 1
	s_waitcnt lgkmcnt(0)
	v_mfma_f32_16x16x32_bf16 v[60:63], v[144:147], v[186:189], v[60:63]
	v_mfma_f32_16x16x32_bf16 v[56:59], v[162:165], v[186:189], v[56:59]
	v_mfma_f32_16x16x32_bf16 v[44:47], v[144:147], v[194:197], v[44:47]
	v_mfma_f32_16x16x32_bf16 v[40:43], v[162:165], v[194:197], v[40:43]
	v_mfma_f32_16x16x32_bf16 v[28:31], v[144:147], v[202:205], v[28:31]
	v_mfma_f32_16x16x32_bf16 v[24:27], v[162:165], v[202:205], v[24:27]
	v_mfma_f32_16x16x32_bf16 v[12:15], v[144:147], v[214:217], v[12:15]
	v_mfma_f32_16x16x32_bf16 v[8:11], v[162:165], v[214:217], v[8:11]
	v_mfma_f32_16x16x32_bf16 v[60:63], v[148:151], v[190:193], v[60:63]
	v_mfma_f32_16x16x32_bf16 v[56:59], v[166:169], v[190:193], v[56:59]
	v_mfma_f32_16x16x32_bf16 v[44:47], v[148:151], v[198:201], v[44:47]
	v_mfma_f32_16x16x32_bf16 v[40:43], v[166:169], v[198:201], v[40:43]
	v_mfma_f32_16x16x32_bf16 v[28:31], v[148:151], v[210:213], v[28:31]
	v_mfma_f32_16x16x32_bf16 v[24:27], v[166:169], v[210:213], v[24:27]
	v_mfma_f32_16x16x32_bf16 v[12:15], v[148:151], v[218:221], v[12:15]
	v_mfma_f32_16x16x32_bf16 v[8:11], v[166:169], v[218:221], v[8:11]
	s_setprio 0
	s_setprio 1
	v_mfma_f32_16x16x32_bf16 v[52:55], v[170:173], v[186:189], v[52:55]
	v_mfma_f32_16x16x32_bf16 v[48:51], v[178:181], v[186:189], v[48:51]
	v_mfma_f32_16x16x32_bf16 v[36:39], v[170:173], v[194:197], v[36:39]
	v_mfma_f32_16x16x32_bf16 v[32:35], v[178:181], v[194:197], v[32:35]
	v_mfma_f32_16x16x32_bf16 v[20:23], v[170:173], v[202:205], v[20:23]
	v_mfma_f32_16x16x32_bf16 v[16:19], v[178:181], v[202:205], v[16:19]
	v_mfma_f32_16x16x32_bf16 v[4:7], v[170:173], v[214:217], v[4:7]
	v_mfma_f32_16x16x32_bf16 v[0:3], v[178:181], v[214:217], v[0:3]
	v_mfma_f32_16x16x32_bf16 v[52:55], v[174:177], v[190:193], v[52:55]
	v_mfma_f32_16x16x32_bf16 v[48:51], v[182:185], v[190:193], v[48:51]
	v_mfma_f32_16x16x32_bf16 v[36:39], v[174:177], v[198:201], v[36:39]
	v_mfma_f32_16x16x32_bf16 v[32:35], v[182:185], v[198:201], v[32:35]
	v_mfma_f32_16x16x32_bf16 v[20:23], v[174:177], v[210:213], v[20:23]
	v_mfma_f32_16x16x32_bf16 v[16:19], v[182:185], v[210:213], v[16:19]
	v_mfma_f32_16x16x32_bf16 v[4:7], v[174:177], v[218:221], v[4:7]
	v_mfma_f32_16x16x32_bf16 v[0:3], v[182:185], v[218:221], v[0:3]
	s_setprio 0
	s_add_i32 s56, s56, 2
	s_add_u32 s26, s26, 0x100
	s_addc_u32 s27, s27, 0
	s_add_u32 s54, s54, 0x100
	s_addc_u32 s55, s55, 0
	s_cmp_gt_u32 s56, 13
	s_cbranch_scc0 .Lrot3_head
	s_barrier
	s_and_b64 vcc, exec, s[16:17]
	s_cbranch_vccz .LBB0_1132
	s_barrier

.LBB0_1209:
	s_add_u32 s53, s26, 0x100
	v_mov_b32_e32 v0, 0
	s_addc_u32 s54, s27, 0
	s_mov_b32 s55, -2
	s_waitcnt lgkmcnt(0)
	v_mov_b32_e32 v1, v0
	v_mov_b32_e32 v2, v0
	v_mov_b32_e32 v3, v0
	v_mov_b32_e32 v4, v0
	v_mov_b32_e32 v5, v0
	v_mov_b32_e32 v6, v0
	v_mov_b32_e32 v7, v0
	v_mov_b32_e32 v16, v0
	v_mov_b32_e32 v17, v0
	v_mov_b32_e32 v18, v0
	v_mov_b32_e32 v19, v0
	s_waitcnt vmcnt(0)
	v_mov_b32_e32 v20, v0
	v_mov_b32_e32 v21, v0
	v_mov_b32_e32 v22, v0
	v_mov_b32_e32 v23, v0
	v_mov_b32_e32 v32, v0
	v_mov_b32_e32 v33, v0
	v_mov_b32_e32 v34, v0
	v_mov_b32_e32 v35, v0
	v_mov_b32_e32 v36, v0
	v_mov_b32_e32 v37, v0
	v_mov_b32_e32 v38, v0
	v_mov_b32_e32 v39, v0
	v_mov_b32_e32 v48, v0
	v_mov_b32_e32 v49, v0
	v_mov_b32_e32 v50, v0
	v_mov_b32_e32 v51, v0
	v_mov_b32_e32 v52, v0
	v_mov_b32_e32 v53, v0
	v_mov_b32_e32 v54, v0
	v_mov_b32_e32 v55, v0
	v_mov_b32_e32 v8, v0
	v_mov_b32_e32 v9, v0
	v_mov_b32_e32 v10, v0
	v_mov_b32_e32 v11, v0
	v_mov_b32_e32 v12, v0
	v_mov_b32_e32 v13, v0
	v_mov_b32_e32 v14, v0
	v_mov_b32_e32 v15, v0
	v_mov_b32_e32 v24, v0
	v_mov_b32_e32 v25, v0
	v_mov_b32_e32 v26, v0
	v_mov_b32_e32 v27, v0
	v_mov_b32_e32 v28, v0
	v_mov_b32_e32 v29, v0
	v_mov_b32_e32 v30, v0
	v_mov_b32_e32 v31, v0
	v_mov_b32_e32 v40, v0
	v_mov_b32_e32 v41, v0
	v_mov_b32_e32 v42, v0
	v_mov_b32_e32 v43, v0
	v_mov_b32_e32 v44, v0
	v_mov_b32_e32 v45, v0
	v_mov_b32_e32 v46, v0
	v_mov_b32_e32 v47, v0
	v_mov_b32_e32 v56, v0
	v_mov_b32_e32 v57, v0
	v_mov_b32_e32 v58, v0
	v_mov_b32_e32 v59, v0
	v_mov_b32_e32 v60, v0
	v_mov_b32_e32 v61, v0
	v_mov_b32_e32 v62, v0
	v_mov_b32_e32 v63, v0
	v_mov_b32_e32 v64, v0
	v_mov_b32_e32 v65, v0
	v_mov_b32_e32 v66, v0
	v_mov_b32_e32 v67, v0
	v_mov_b32_e32 v68, v0
	v_mov_b32_e32 v69, v0
	v_mov_b32_e32 v70, v0
	v_mov_b32_e32 v71, v0
	v_mov_b32_e32 v80, v0
	v_mov_b32_e32 v81, v0
	v_mov_b32_e32 v82, v0
	v_mov_b32_e32 v83, v0
	v_mov_b32_e32 v84, v0
	v_mov_b32_e32 v85, v0
	v_mov_b32_e32 v86, v0
	v_mov_b32_e32 v87, v0
	v_mov_b32_e32 v96, v0
	v_mov_b32_e32 v97, v0
	v_mov_b32_e32 v98, v0
	v_mov_b32_e32 v99, v0
	v_mov_b32_e32 v100, v0
	v_mov_b32_e32 v101, v0
	v_mov_b32_e32 v102, v0
	v_mov_b32_e32 v103, v0
	v_mov_b32_e32 v112, v0
	v_mov_b32_e32 v113, v0
	v_mov_b32_e32 v114, v0
	v_mov_b32_e32 v115, v0
	v_mov_b32_e32 v116, v0
	v_mov_b32_e32 v117, v0
	v_mov_b32_e32 v118, v0
	v_mov_b32_e32 v119, v0
	v_mov_b32_e32 v72, v0
	v_mov_b32_e32 v73, v0
	v_mov_b32_e32 v74, v0
	v_mov_b32_e32 v75, v0
	v_mov_b32_e32 v76, v0
	v_mov_b32_e32 v77, v0
	v_mov_b32_e32 v78, v0
	v_mov_b32_e32 v79, v0
	v_mov_b32_e32 v88, v0
	v_mov_b32_e32 v89, v0
	v_mov_b32_e32 v90, v0
	v_mov_b32_e32 v91, v0
	v_mov_b32_e32 v92, v0
	v_mov_b32_e32 v93, v0
	v_mov_b32_e32 v94, v0
	v_mov_b32_e32 v95, v0
	v_mov_b32_e32 v104, v0
	v_mov_b32_e32 v105, v0
	v_mov_b32_e32 v106, v0
	v_mov_b32_e32 v107, v0
	v_mov_b32_e32 v108, v0
	v_mov_b32_e32 v109, v0
	v_mov_b32_e32 v110, v0
	v_mov_b32_e32 v111, v0
	v_mov_b32_e32 v120, v0
	v_mov_b32_e32 v121, v0
	v_mov_b32_e32 v122, v0
	v_mov_b32_e32 v123, v0
	v_mov_b32_e32 v124, v0
	v_mov_b32_e32 v125, v0
	v_mov_b32_e32 v126, v0
	v_mov_b32_e32 v127, v0
	s_branch .LBB0_1210

.LBB0_1210:
	ds_read_b128 v[128:131], v189
	ds_read_b128 v[132:135], v189 offset:1024
	ds_read_b128 v[136:139], v189 offset:2048
	ds_read_b128 v[140:143], v189 offset:3072
	ds_read_b128 v[144:147], v190
	ds_read_b128 v[148:151], v190 offset:1024
	ds_read_b128 v[168:171], v190 offset:2048
	ds_read_b128 v[172:175], v190 offset:3072
	s_add_u32 s26, s24, 0x100
	s_addc_u32 s27, s25, 0
	s_cmp_eq_u32 s55, 40
	s_cselect_b32 s31, s5, s27
	s_cselect_b32 s30, s4, s26
	s_cselect_b32 s29, s23, s54
	s_cselect_b32 s28, s22, s53
	v_lshl_add_u64 v[184:185], s[24:25], 0, v[160:161]
	s_add_i32 m0, s37, 0xc000
	ds_read_b128 v[176:179], v191
	ds_read_b128 v[180:183], v191 offset:1024
	ds_read_b128 v[194:197], v191 offset:2048
	ds_read_b128 v[198:201], v191 offset:3072
	ds_read_b128 v[202:205], v191 offset:4096
	ds_read_b128 v[210:213], v191 offset:5120
	ds_read_b128 v[214:217], v191 offset:6144
	ds_read_b128 v[218:221], v191 offset:7168
	global_load_lds_dwordx4 v[184:185], off
	v_lshl_add_u64 v[184:185], s[24:25], 0, v[162:163]
	s_add_i32 m0, s37, 0xe000
	s_nop 0
	global_load_lds_dwordx4 v[184:185], off
	s_waitcnt vmcnt(8)
	s_waitcnt lgkmcnt(0)
	s_barrier
	s_setprio 1
	s_waitcnt lgkmcnt(0)
	v_mfma_f32_16x16x32_bf16 v[124:127], v[128:131], v[176:179], v[124:127]
	v_mfma_f32_16x16x32_bf16 v[120:123], v[136:139], v[176:179], v[120:123]
	v_mfma_f32_16x16x32_bf16 v[108:111], v[128:131], v[194:197], v[108:111]
	v_mfma_f32_16x16x32_bf16 v[104:107], v[136:139], v[194:197], v[104:107]
	v_mfma_f32_16x16x32_bf16 v[92:95], v[128:131], v[202:205], v[92:95]
	v_mfma_f32_16x16x32_bf16 v[88:91], v[136:139], v[202:205], v[88:91]
	v_mfma_f32_16x16x32_bf16 v[76:79], v[128:131], v[214:217], v[76:79]
	v_mfma_f32_16x16x32_bf16 v[72:75], v[136:139], v[214:217], v[72:75]
	v_mfma_f32_16x16x32_bf16 v[124:127], v[132:135], v[180:183], v[124:127]
	v_mfma_f32_16x16x32_bf16 v[120:123], v[140:143], v[180:183], v[120:123]
	v_mfma_f32_16x16x32_bf16 v[108:111], v[132:135], v[198:201], v[108:111]
	v_mfma_f32_16x16x32_bf16 v[104:107], v[140:143], v[198:201], v[104:107]
	v_mfma_f32_16x16x32_bf16 v[92:95], v[132:135], v[210:213], v[92:95]
	v_mfma_f32_16x16x32_bf16 v[88:91], v[140:143], v[210:213], v[88:91]
	v_mfma_f32_16x16x32_bf16 v[76:79], v[132:135], v[218:221], v[76:79]
	v_mfma_f32_16x16x32_bf16 v[72:75], v[140:143], v[218:221], v[72:75]
	s_setprio 0
	s_setprio 1
	v_mfma_f32_16x16x32_bf16 v[116:119], v[144:147], v[176:179], v[116:119]
	v_mfma_f32_16x16x32_bf16 v[112:115], v[168:171], v[176:179], v[112:115]
	v_mfma_f32_16x16x32_bf16 v[100:103], v[144:147], v[194:197], v[100:103]
	v_mfma_f32_16x16x32_bf16 v[96:99], v[168:171], v[194:197], v[96:99]
	v_mfma_f32_16x16x32_bf16 v[84:87], v[144:147], v[202:205], v[84:87]
	v_mfma_f32_16x16x32_bf16 v[80:83], v[168:171], v[202:205], v[80:83]
	v_mfma_f32_16x16x32_bf16 v[68:71], v[144:147], v[214:217], v[68:71]
	v_mfma_f32_16x16x32_bf16 v[64:67], v[168:171], v[214:217], v[64:67]
	v_mfma_f32_16x16x32_bf16 v[116:119], v[148:151], v[180:183], v[116:119]
	v_mfma_f32_16x16x32_bf16 v[112:115], v[172:175], v[180:183], v[112:115]
	v_mfma_f32_16x16x32_bf16 v[100:103], v[148:151], v[198:201], v[100:103]
	v_mfma_f32_16x16x32_bf16 v[96:99], v[172:175], v[198:201], v[96:99]
	v_mfma_f32_16x16x32_bf16 v[84:87], v[148:151], v[210:213], v[84:87]
	v_mfma_f32_16x16x32_bf16 v[80:83], v[172:175], v[210:213], v[80:83]
	v_mfma_f32_16x16x32_bf16 v[68:71], v[148:151], v[218:221], v[68:71]
	v_mfma_f32_16x16x32_bf16 v[64:67], v[172:175], v[218:221], v[64:67]
	s_setprio 0
	s_barrier
	s_add_i32 s24, s47, s36
	v_lshl_add_u64 v[184:185], s[28:29], 0, v[154:155]
	s_mov_b32 m0, s24
	ds_read_b128 v[176:179], v191 offset:16384
	ds_read_b128 v[180:183], v191 offset:17408
	ds_read_b128 v[194:197], v191 offset:18432
	ds_read_b128 v[198:201], v191 offset:19456
	ds_read_b128 v[202:205], v191 offset:20480
	ds_read_b128 v[210:213], v191 offset:21504
	ds_read_b128 v[214:217], v191 offset:22528
	ds_read_b128 v[218:221], v191 offset:23552
	global_load_lds_dwordx4 v[184:185], off
	s_add_i32 m0, s24, 0x2000
	s_add_u32 s24, s28, 0xb0000
	v_lshl_add_u64 v[206:207], s[28:29], 0, v[158:159]
	s_addc_u32 s25, s29, 0
	s_add_i32 s56, s48, s36
	global_load_lds_dwordx4 v[206:207], off
	v_lshl_add_u64 v[222:223], s[24:25], 0, v[154:155]
	s_mov_b32 m0, s56
	v_lshl_add_u64 v[224:225], s[30:31], 0, v[156:157]
	global_load_lds_dwordx4 v[222:223], off
	v_lshl_add_u64 v[222:223], s[24:25], 0, v[158:159]
	s_add_i32 m0, s56, 0x2000
	s_nop 0
	global_load_lds_dwordx4 v[222:223], off
	v_lshl_add_u64 v[222:223], s[30:31], 0, v[152:153]
	s_mov_b32 m0, s37
	s_nop 0
	global_load_lds_dwordx4 v[222:223], off
	s_mov_b32 m0, s38
	s_nop 0
	global_load_lds_dwordx4 v[224:225], off
	s_waitcnt vmcnt(8)
	s_waitcnt lgkmcnt(0)
	s_barrier
	s_setprio 1
	s_waitcnt lgkmcnt(0)
	v_mfma_f32_16x16x32_bf16 v[60:63], v[128:131], v[176:179], v[60:63]
	v_mfma_f32_16x16x32_bf16 v[56:59], v[136:139], v[176:179], v[56:59]
	v_mfma_f32_16x16x32_bf16 v[44:47], v[128:131], v[194:197], v[44:47]
	v_mfma_f32_16x16x32_bf16 v[40:43], v[136:139], v[194:197], v[40:43]
	v_mfma_f32_16x16x32_bf16 v[28:31], v[128:131], v[202:205], v[28:31]
	v_mfma_f32_16x16x32_bf16 v[24:27], v[136:139], v[202:205], v[24:27]
	v_mfma_f32_16x16x32_bf16 v[12:15], v[128:131], v[214:217], v[12:15]
	v_mfma_f32_16x16x32_bf16 v[8:11], v[136:139], v[214:217], v[8:11]
	v_mfma_f32_16x16x32_bf16 v[60:63], v[132:135], v[180:183], v[60:63]
	v_mfma_f32_16x16x32_bf16 v[56:59], v[140:143], v[180:183], v[56:59]
	v_mfma_f32_16x16x32_bf16 v[44:47], v[132:135], v[198:201], v[44:47]
	v_mfma_f32_16x16x32_bf16 v[40:43], v[140:143], v[198:201], v[40:43]
	v_mfma_f32_16x16x32_bf16 v[28:31], v[132:135], v[210:213], v[28:31]
	v_mfma_f32_16x16x32_bf16 v[24:27], v[140:143], v[210:213], v[24:27]
	v_mfma_f32_16x16x32_bf16 v[12:15], v[132:135], v[218:221], v[12:15]
	v_mfma_f32_16x16x32_bf16 v[8:11], v[140:143], v[218:221], v[8:11]
	s_setprio 0
	s_setprio 1
	v_mfma_f32_16x16x32_bf16 v[52:55], v[144:147], v[176:179], v[52:55]
	v_mfma_f32_16x16x32_bf16 v[48:51], v[168:171], v[176:179], v[48:51]
	v_mfma_f32_16x16x32_bf16 v[36:39], v[144:147], v[194:197], v[36:39]
	v_mfma_f32_16x16x32_bf16 v[32:35], v[168:171], v[194:197], v[32:35]
	v_mfma_f32_16x16x32_bf16 v[20:23], v[144:147], v[202:205], v[20:23]
	v_mfma_f32_16x16x32_bf16 v[16:19], v[168:171], v[202:205], v[16:19]
	v_mfma_f32_16x16x32_bf16 v[4:7], v[144:147], v[214:217], v[4:7]
	v_mfma_f32_16x16x32_bf16 v[0:3], v[168:171], v[214:217], v[0:3]
	v_mfma_f32_16x16x32_bf16 v[52:55], v[148:151], v[180:183], v[52:55]
	v_mfma_f32_16x16x32_bf16 v[48:51], v[172:175], v[180:183], v[48:51]
	v_mfma_f32_16x16x32_bf16 v[36:39], v[148:151], v[198:201], v[36:39]
	v_mfma_f32_16x16x32_bf16 v[32:35], v[172:175], v[198:201], v[32:35]
	v_mfma_f32_16x16x32_bf16 v[20:23], v[148:151], v[210:213], v[20:23]
	v_mfma_f32_16x16x32_bf16 v[16:19], v[172:175], v[210:213], v[16:19]
	v_mfma_f32_16x16x32_bf16 v[4:7], v[148:151], v[218:221], v[4:7]
	v_mfma_f32_16x16x32_bf16 v[0:3], v[172:175], v[218:221], v[0:3]
	s_setprio 0
	s_barrier
	s_add_i32 s56, 0, 0x18000
	s_add_i32 s57, 0, 0x1c000
	v_add_u32_e32 v140, s56, v187
	v_add_u32_e32 v172, s57, v187
	ds_read_b128 v[128:131], v140
	ds_read_b128 v[132:135], v140 offset:1024
	ds_read_b128 v[136:139], v140 offset:2048
	ds_read_b128 v[140:143], v140 offset:3072
	ds_read_b128 v[144:147], v172
	ds_read_b128 v[148:151], v172 offset:1024
	ds_read_b128 v[168:171], v172 offset:2048
	ds_read_b128 v[172:175], v172 offset:3072
	s_add_u32 s24, s30, 0xb0000
	s_addc_u32 s25, s31, 0
	s_mov_b32 m0, s39
	v_lshl_add_u64 v[226:227], s[24:25], 0, v[152:153]
	ds_read_b128 v[176:179], v191 offset:32768
	ds_read_b128 v[180:183], v191 offset:33792
	ds_read_b128 v[194:197], v191 offset:34816
	ds_read_b128 v[198:201], v191 offset:35840
	ds_read_b128 v[202:205], v191 offset:36864
	ds_read_b128 v[210:213], v191 offset:37888
	ds_read_b128 v[214:217], v191 offset:38912
	ds_read_b128 v[218:221], v191 offset:39936
	global_load_lds_dwordx4 v[226:227], off
	v_lshl_add_u64 v[226:227], s[24:25], 0, v[156:157]
	s_mov_b32 m0, s40
	s_nop 0
	global_load_lds_dwordx4 v[226:227], off
	s_waitcnt vmcnt(8)
	s_waitcnt lgkmcnt(0)
	s_barrier
	s_setprio 1
	s_waitcnt lgkmcnt(0)
	v_mfma_f32_16x16x32_bf16 v[124:127], v[128:131], v[176:179], v[124:127]
	v_mfma_f32_16x16x32_bf16 v[120:123], v[136:139], v[176:179], v[120:123]
	v_mfma_f32_16x16x32_bf16 v[108:111], v[128:131], v[194:197], v[108:111]
	v_mfma_f32_16x16x32_bf16 v[104:107], v[136:139], v[194:197], v[104:107]
	v_mfma_f32_16x16x32_bf16 v[92:95], v[128:131], v[202:205], v[92:95]
	v_mfma_f32_16x16x32_bf16 v[88:91], v[136:139], v[202:205], v[88:91]
	v_mfma_f32_16x16x32_bf16 v[76:79], v[128:131], v[214:217], v[76:79]
	v_mfma_f32_16x16x32_bf16 v[72:75], v[136:139], v[214:217], v[72:75]
	v_mfma_f32_16x16x32_bf16 v[124:127], v[132:135], v[180:183], v[124:127]
	v_mfma_f32_16x16x32_bf16 v[120:123], v[140:143], v[180:183], v[120:123]
	v_mfma_f32_16x16x32_bf16 v[108:111], v[132:135], v[198:201], v[108:111]
	v_mfma_f32_16x16x32_bf16 v[104:107], v[140:143], v[198:201], v[104:107]
	v_mfma_f32_16x16x32_bf16 v[92:95], v[132:135], v[210:213], v[92:95]
	v_mfma_f32_16x16x32_bf16 v[88:91], v[140:143], v[210:213], v[88:91]
	v_mfma_f32_16x16x32_bf16 v[76:79], v[132:135], v[218:221], v[76:79]
	v_mfma_f32_16x16x32_bf16 v[72:75], v[140:143], v[218:221], v[72:75]
	s_setprio 0
	s_setprio 1
	v_mfma_f32_16x16x32_bf16 v[116:119], v[144:147], v[176:179], v[116:119]
	v_mfma_f32_16x16x32_bf16 v[112:115], v[168:171], v[176:179], v[112:115]
	v_mfma_f32_16x16x32_bf16 v[100:103], v[144:147], v[194:197], v[100:103]
	v_mfma_f32_16x16x32_bf16 v[96:99], v[168:171], v[194:197], v[96:99]
	v_mfma_f32_16x16x32_bf16 v[84:87], v[144:147], v[202:205], v[84:87]
	v_mfma_f32_16x16x32_bf16 v[80:83], v[168:171], v[202:205], v[80:83]
	v_mfma_f32_16x16x32_bf16 v[68:71], v[144:147], v[214:217], v[68:71]
	v_mfma_f32_16x16x32_bf16 v[64:67], v[168:171], v[214:217], v[64:67]
	v_mfma_f32_16x16x32_bf16 v[116:119], v[148:151], v[180:183], v[116:119]
	v_mfma_f32_16x16x32_bf16 v[112:115], v[172:175], v[180:183], v[112:115]
	v_mfma_f32_16x16x32_bf16 v[100:103], v[148:151], v[198:201], v[100:103]
	v_mfma_f32_16x16x32_bf16 v[96:99], v[172:175], v[198:201], v[96:99]
	v_mfma_f32_16x16x32_bf16 v[84:87], v[148:151], v[210:213], v[84:87]
	v_mfma_f32_16x16x32_bf16 v[80:83], v[172:175], v[210:213], v[80:83]
	v_mfma_f32_16x16x32_bf16 v[68:71], v[148:151], v[218:221], v[68:71]
	v_mfma_f32_16x16x32_bf16 v[64:67], v[172:175], v[218:221], v[64:67]
	s_setprio 0
	s_barrier
	s_add_i32 s24, s56, s36
	v_lshl_add_u64 v[184:185], v[184:185], 0, s[18:19]
	s_mov_b32 m0, s24
	ds_read_b128 v[176:179], v191 offset:49152
	ds_read_b128 v[180:183], v191 offset:50176
	ds_read_b128 v[194:197], v191 offset:51200
	ds_read_b128 v[198:201], v191 offset:52224
	ds_read_b128 v[202:205], v191 offset:53248
	ds_read_b128 v[210:213], v191 offset:54272
	ds_read_b128 v[214:217], v191 offset:55296
	ds_read_b128 v[218:221], v191 offset:56320
	global_load_lds_dwordx4 v[184:185], off
	s_add_i32 m0, s24, 0x2000
	s_add_u32 s24, s28, 0xb0080
	v_lshl_add_u64 v[184:185], v[206:207], 0, s[18:19]
	s_addc_u32 s25, s29, 0
	s_add_i32 s28, s57, s36
	global_load_lds_dwordx4 v[184:185], off
	v_lshl_add_u64 v[184:185], s[24:25], 0, v[154:155]
	s_mov_b32 m0, s28
	s_nop 0
	global_load_lds_dwordx4 v[184:185], off
	v_lshl_add_u64 v[184:185], s[24:25], 0, v[158:159]
	s_add_i32 m0, s28, 0x2000
	s_nop 0
	global_load_lds_dwordx4 v[184:185], off
	v_lshl_add_u64 v[184:185], v[222:223], 0, s[18:19]
	s_mov_b32 m0, s42
	s_nop 0
	global_load_lds_dwordx4 v[184:185], off
	v_lshl_add_u64 v[184:185], v[224:225], 0, s[18:19]
	s_mov_b32 m0, s43
	s_nop 0
	global_load_lds_dwordx4 v[184:185], off
	s_waitcnt vmcnt(8)
	s_waitcnt lgkmcnt(0)
	s_barrier
	s_setprio 1
	s_waitcnt lgkmcnt(0)
	v_mfma_f32_16x16x32_bf16 v[60:63], v[128:131], v[176:179], v[60:63]
	v_mfma_f32_16x16x32_bf16 v[56:59], v[136:139], v[176:179], v[56:59]
	v_mfma_f32_16x16x32_bf16 v[44:47], v[128:131], v[194:197], v[44:47]
	v_mfma_f32_16x16x32_bf16 v[40:43], v[136:139], v[194:197], v[40:43]
	v_mfma_f32_16x16x32_bf16 v[28:31], v[128:131], v[202:205], v[28:31]
	v_mfma_f32_16x16x32_bf16 v[24:27], v[136:139], v[202:205], v[24:27]
	v_mfma_f32_16x16x32_bf16 v[12:15], v[128:131], v[214:217], v[12:15]
	v_mfma_f32_16x16x32_bf16 v[8:11], v[136:139], v[214:217], v[8:11]
	v_mfma_f32_16x16x32_bf16 v[60:63], v[132:135], v[180:183], v[60:63]
	v_mfma_f32_16x16x32_bf16 v[56:59], v[140:143], v[180:183], v[56:59]
	v_mfma_f32_16x16x32_bf16 v[44:47], v[132:135], v[198:201], v[44:47]
	v_mfma_f32_16x16x32_bf16 v[40:43], v[140:143], v[198:201], v[40:43]
	v_mfma_f32_16x16x32_bf16 v[28:31], v[132:135], v[210:213], v[28:31]
	v_mfma_f32_16x16x32_bf16 v[24:27], v[140:143], v[210:213], v[24:27]
	v_mfma_f32_16x16x32_bf16 v[12:15], v[132:135], v[218:221], v[12:15]
	v_mfma_f32_16x16x32_bf16 v[8:11], v[140:143], v[218:221], v[8:11]
	s_setprio 0
	s_setprio 1
	v_mfma_f32_16x16x32_bf16 v[52:55], v[144:147], v[176:179], v[52:55]
	v_mfma_f32_16x16x32_bf16 v[48:51], v[168:171], v[176:179], v[48:51]
	v_mfma_f32_16x16x32_bf16 v[36:39], v[144:147], v[194:197], v[36:39]
	v_mfma_f32_16x16x32_bf16 v[32:35], v[168:171], v[194:197], v[32:35]
	v_mfma_f32_16x16x32_bf16 v[20:23], v[144:147], v[202:205], v[20:23]
	v_mfma_f32_16x16x32_bf16 v[16:19], v[168:171], v[202:205], v[16:19]
	v_mfma_f32_16x16x32_bf16 v[4:7], v[144:147], v[214:217], v[4:7]
	v_mfma_f32_16x16x32_bf16 v[0:3], v[168:171], v[214:217], v[0:3]
	v_mfma_f32_16x16x32_bf16 v[52:55], v[148:151], v[180:183], v[52:55]
	v_mfma_f32_16x16x32_bf16 v[48:51], v[172:175], v[180:183], v[48:51]
	v_mfma_f32_16x16x32_bf16 v[36:39], v[148:151], v[198:201], v[36:39]
	v_mfma_f32_16x16x32_bf16 v[32:35], v[172:175], v[198:201], v[32:35]
	v_mfma_f32_16x16x32_bf16 v[20:23], v[148:151], v[210:213], v[20:23]
	v_mfma_f32_16x16x32_bf16 v[16:19], v[172:175], v[210:213], v[16:19]
	v_mfma_f32_16x16x32_bf16 v[4:7], v[148:151], v[218:221], v[4:7]
	v_mfma_f32_16x16x32_bf16 v[0:3], v[172:175], v[218:221], v[0:3]
	s_setprio 0
	s_add_i32 s55, s55, 2
	s_add_u32 s53, s53, 0x100
	s_addc_u32 s54, s54, 0
	s_cmp_gt_u32 s55, 41
	s_mov_b64 s[24:25], s[26:27]
	s_cbranch_scc0 .Lrot4_head
	s_barrier
	s_and_b64 vcc, exec, s[20:21]
	s_cbranch_vccz .LBB0_1213
	s_barrier
